# GEMM K loops: per-cluster setprio toggles replaced by one static priority raise of the trailing half-workgroup (waves 4..7) for the loop
# speedup vs baseline: 1.0038x; 1.0038x over previous
.LBB0_162:
	s_ashr_i32 s15, s14, 31
	s_lshl_b64 s[16:17], s[14:15], 20
	s_add_u32 s16, s29, s16
	s_addc_u32 s17, s30, s17
	s_and_b64 s[18:19], s[0:1], exec
	s_cselect_b32 s15, s17, s23
	s_cselect_b32 s54, s16, s22
	s_ashr_i32 s13, s12, 31
	s_lshl_b64 s[18:19], s[12:13], 22
	s_add_u32 s13, s8, s18
	s_addc_u32 s26, s9, s19
	s_ashr_i32 s18, s14, 3
	s_ashr_i32 s19, s18, 31
	s_lshl_b64 s[18:19], s[18:19], 12
	s_add_u32 s18, s13, s18
	s_addc_u32 s19, s26, s19
	s_and_b64 s[26:27], s[0:1], exec
	s_cselect_b32 s13, s19, s25
	s_cselect_b32 s55, s18, s24
	s_add_u32 s22, s22, 0x80080
	s_addc_u32 s23, s23, 0
	s_add_u32 s56, s24, 0x100
	v_mov_b32_e32 v0, 0
	s_addc_u32 s57, s25, 0
	s_mov_b32 s58, -2
	v_mov_b32_e32 v1, v0
	v_mov_b32_e32 v2, v0
	v_mov_b32_e32 v3, v0
	v_mov_b32_e32 v4, v0
	v_mov_b32_e32 v5, v0
	v_mov_b32_e32 v6, v0
	v_mov_b32_e32 v7, v0
	v_mov_b32_e32 v8, v0
	v_mov_b32_e32 v9, v0
	v_mov_b32_e32 v10, v0
	v_mov_b32_e32 v11, v0
	v_mov_b32_e32 v16, v0
	v_mov_b32_e32 v17, v0
	v_mov_b32_e32 v18, v0
	v_mov_b32_e32 v19, v0
	v_mov_b32_e32 v24, v0
	v_mov_b32_e32 v25, v0
	v_mov_b32_e32 v26, v0
	v_mov_b32_e32 v27, v0
	v_mov_b32_e32 v32, v0
	v_mov_b32_e32 v33, v0
	v_mov_b32_e32 v34, v0
	v_mov_b32_e32 v35, v0
	v_mov_b32_e32 v40, v0
	v_mov_b32_e32 v41, v0
	v_mov_b32_e32 v42, v0
	v_mov_b32_e32 v43, v0
	v_mov_b32_e32 v48, v0
	v_mov_b32_e32 v49, v0
	v_mov_b32_e32 v50, v0
	v_mov_b32_e32 v51, v0
	v_mov_b32_e32 v12, v0
	v_mov_b32_e32 v13, v0
	v_mov_b32_e32 v14, v0
	v_mov_b32_e32 v15, v0
	v_mov_b32_e32 v20, v0
	v_mov_b32_e32 v21, v0
	v_mov_b32_e32 v22, v0
	v_mov_b32_e32 v23, v0
	v_mov_b32_e32 v28, v0
	v_mov_b32_e32 v29, v0
	v_mov_b32_e32 v30, v0
	v_mov_b32_e32 v31, v0
	v_mov_b32_e32 v36, v0
	v_mov_b32_e32 v37, v0
	v_mov_b32_e32 v38, v0
	v_mov_b32_e32 v39, v0
	v_mov_b32_e32 v44, v0
	v_mov_b32_e32 v45, v0
	v_mov_b32_e32 v46, v0
	v_mov_b32_e32 v47, v0
	v_mov_b32_e32 v52, v0
	v_mov_b32_e32 v53, v0
	v_mov_b32_e32 v54, v0
	v_mov_b32_e32 v55, v0
	v_mov_b32_e32 v56, v0
	v_mov_b32_e32 v57, v0
	v_mov_b32_e32 v58, v0
	v_mov_b32_e32 v59, v0
	v_mov_b32_e32 v60, v0
	v_mov_b32_e32 v61, v0
	v_mov_b32_e32 v62, v0
	v_mov_b32_e32 v63, v0
	v_mov_b32_e32 v64, v0
	v_mov_b32_e32 v65, v0
	v_mov_b32_e32 v66, v0
	v_mov_b32_e32 v67, v0
	v_mov_b32_e32 v68, v0
	v_mov_b32_e32 v69, v0
	v_mov_b32_e32 v70, v0
	v_mov_b32_e32 v71, v0
	v_mov_b32_e32 v72, v0
	v_mov_b32_e32 v73, v0
	v_mov_b32_e32 v74, v0
	v_mov_b32_e32 v75, v0
	v_mov_b32_e32 v80, v0
	v_mov_b32_e32 v81, v0
	v_mov_b32_e32 v82, v0
	v_mov_b32_e32 v83, v0
	v_mov_b32_e32 v88, v0
	v_mov_b32_e32 v89, v0
	v_mov_b32_e32 v90, v0
	v_mov_b32_e32 v91, v0
	v_mov_b32_e32 v96, v0
	v_mov_b32_e32 v97, v0
	v_mov_b32_e32 v98, v0
	v_mov_b32_e32 v99, v0
	v_mov_b32_e32 v104, v0
	v_mov_b32_e32 v105, v0
	v_mov_b32_e32 v106, v0
	v_mov_b32_e32 v107, v0
	v_mov_b32_e32 v112, v0
	v_mov_b32_e32 v113, v0
	v_mov_b32_e32 v114, v0
	v_mov_b32_e32 v115, v0
	v_mov_b32_e32 v76, v0
	v_mov_b32_e32 v77, v0
	v_mov_b32_e32 v78, v0
	v_mov_b32_e32 v79, v0
	v_mov_b32_e32 v84, v0
	v_mov_b32_e32 v85, v0
	v_mov_b32_e32 v86, v0
	v_mov_b32_e32 v87, v0
	v_mov_b32_e32 v92, v0
	v_mov_b32_e32 v93, v0
	v_mov_b32_e32 v94, v0
	v_mov_b32_e32 v95, v0
	v_mov_b32_e32 v100, v0
	v_mov_b32_e32 v101, v0
	v_mov_b32_e32 v102, v0
	v_mov_b32_e32 v103, v0
	v_mov_b32_e32 v108, v0
	v_mov_b32_e32 v109, v0
	v_mov_b32_e32 v110, v0
	v_mov_b32_e32 v111, v0
	v_mov_b32_e32 v116, v0
	v_mov_b32_e32 v117, v0
	v_mov_b32_e32 v118, v0
	v_mov_b32_e32 v119, v0
	v_mov_b32_e32 v120, v0
	v_mov_b32_e32 v121, v0
	v_mov_b32_e32 v122, v0
	v_mov_b32_e32 v123, v0
	v_mov_b32_e32 v124, v0
	v_mov_b32_e32 v125, v0
	v_mov_b32_e32 v126, v0
	v_mov_b32_e32 v127, v0
	s_cmp_lt_u32 s89, 4
	s_cbranch_scc1 .Lprio_163
	s_setprio 1
.Lprio_163:
.LBB0_163:
	ds_read_b128 v[152:155], v149
	ds_read_b128 v[156:159], v149 offset:1024
	ds_read_b128 v[160:163], v149 offset:2048
	ds_read_b128 v[164:167], v149 offset:3072
	ds_read_b128 v[168:171], v150
	ds_read_b128 v[172:175], v150 offset:1024
	ds_read_b128 v[176:179], v150 offset:2048
	ds_read_b128 v[180:183], v150 offset:3072
	s_add_u32 s24, s22, 0xfff80080
	s_addc_u32 s25, s23, -1
	s_cmp_eq_u32 s58, 28
	s_cselect_b32 s27, s15, s25
	s_cselect_b32 s26, s54, s24
	s_cselect_b32 s25, s13, s57
	s_cselect_b32 s24, s55, s56
	s_add_u32 s98, s24, s6
	s_addc_u32 s99, s25, s7
	s_add_u32 s100, s26, s6
	s_addc_u32 s101, s27, s7
	s_add_i32 m0, s21, 0xc000
	ds_read_b128 v[184:187], v151
	ds_read_b128 v[188:191], v151 offset:1024
	ds_read_b128 v[192:195], v151 offset:2048
	ds_read_b128 v[196:199], v151 offset:3072
	ds_read_b128 v[200:203], v151 offset:4096
	ds_read_b128 v[204:207], v151 offset:5120
	ds_read_b128 v[208:211], v151 offset:6144
	ds_read_b128 v[212:215], v151 offset:7168
	global_load_lds_dwordx4 v136, s[22:23]
	s_add_i32 m0, s21, 0xe000
	s_nop 0
	global_load_lds_dwordx4 v138, s[22:23]
	s_waitcnt vmcnt(8)
	s_waitcnt lgkmcnt(0)
	s_barrier
	s_waitcnt lgkmcnt(0)
	v_mfma_f32_16x16x32_bf16 v[124:127], v[152:155], v[184:187], v[124:127]
	v_mfma_f32_16x16x32_bf16 v[120:123], v[160:163], v[184:187], v[120:123]
	v_mfma_f32_16x16x32_bf16 v[116:119], v[152:155], v[192:195], v[116:119]
	v_mfma_f32_16x16x32_bf16 v[108:111], v[160:163], v[192:195], v[108:111]
	v_mfma_f32_16x16x32_bf16 v[100:103], v[152:155], v[200:203], v[100:103]
	v_mfma_f32_16x16x32_bf16 v[92:95], v[160:163], v[200:203], v[92:95]
	v_mfma_f32_16x16x32_bf16 v[84:87], v[152:155], v[208:211], v[84:87]
	v_mfma_f32_16x16x32_bf16 v[76:79], v[160:163], v[208:211], v[76:79]
	v_mfma_f32_16x16x32_bf16 v[124:127], v[156:159], v[188:191], v[124:127]
	v_mfma_f32_16x16x32_bf16 v[120:123], v[164:167], v[188:191], v[120:123]
	v_mfma_f32_16x16x32_bf16 v[116:119], v[156:159], v[196:199], v[116:119]
	v_mfma_f32_16x16x32_bf16 v[108:111], v[164:167], v[196:199], v[108:111]
	v_mfma_f32_16x16x32_bf16 v[100:103], v[156:159], v[204:207], v[100:103]
	v_mfma_f32_16x16x32_bf16 v[92:95], v[164:167], v[204:207], v[92:95]
	v_mfma_f32_16x16x32_bf16 v[84:87], v[156:159], v[212:215], v[84:87]
	v_mfma_f32_16x16x32_bf16 v[76:79], v[164:167], v[212:215], v[76:79]
	v_mfma_f32_16x16x32_bf16 v[112:115], v[168:171], v[184:187], v[112:115]
	v_mfma_f32_16x16x32_bf16 v[104:107], v[176:179], v[184:187], v[104:107]
	v_mfma_f32_16x16x32_bf16 v[96:99], v[168:171], v[192:195], v[96:99]
	v_mfma_f32_16x16x32_bf16 v[88:91], v[176:179], v[192:195], v[88:91]
	v_mfma_f32_16x16x32_bf16 v[80:83], v[168:171], v[200:203], v[80:83]
	v_mfma_f32_16x16x32_bf16 v[72:75], v[176:179], v[200:203], v[72:75]
	v_mfma_f32_16x16x32_bf16 v[68:71], v[168:171], v[208:211], v[68:71]
	v_mfma_f32_16x16x32_bf16 v[64:67], v[176:179], v[208:211], v[64:67]
	v_mfma_f32_16x16x32_bf16 v[112:115], v[172:175], v[188:191], v[112:115]
	v_mfma_f32_16x16x32_bf16 v[104:107], v[180:183], v[188:191], v[104:107]
	v_mfma_f32_16x16x32_bf16 v[96:99], v[172:175], v[196:199], v[96:99]
	v_mfma_f32_16x16x32_bf16 v[88:91], v[180:183], v[196:199], v[88:91]
	v_mfma_f32_16x16x32_bf16 v[80:83], v[172:175], v[204:207], v[80:83]
	v_mfma_f32_16x16x32_bf16 v[72:75], v[180:183], v[204:207], v[72:75]
	v_mfma_f32_16x16x32_bf16 v[68:71], v[172:175], v[212:215], v[68:71]
	v_mfma_f32_16x16x32_bf16 v[64:67], v[180:183], v[212:215], v[64:67]
	s_barrier
	s_add_i32 s59, s43, s28
	s_mov_b32 m0, s59
	ds_read_b128 v[184:187], v151 offset:16384
	ds_read_b128 v[188:191], v151 offset:17408
	ds_read_b128 v[192:195], v151 offset:18432
	ds_read_b128 v[196:199], v151 offset:19456
	ds_read_b128 v[200:203], v151 offset:20480
	ds_read_b128 v[204:207], v151 offset:21504
	ds_read_b128 v[208:211], v151 offset:22528
	ds_read_b128 v[212:215], v151 offset:23552
	global_load_lds_dwordx4 v130, s[24:25]
	s_add_i32 m0, s59, 0x2000
	s_add_u32 s62, s24, 0x200000
	s_addc_u32 s63, s25, 0
	s_add_i32 s59, s48, s28
	global_load_lds_dwordx4 v134, s[24:25]
	s_mov_b32 m0, s59
	s_nop 0
	global_load_lds_dwordx4 v130, s[62:63]
	s_add_i32 m0, s59, 0x2000
	s_nop 0
	global_load_lds_dwordx4 v134, s[62:63]
	s_mov_b32 m0, s21
	s_nop 0
	global_load_lds_dwordx4 v128, s[26:27]
	s_mov_b32 m0, s31
	s_nop 0
	global_load_lds_dwordx4 v132, s[26:27]
	s_waitcnt vmcnt(8)
	s_waitcnt lgkmcnt(0)
	s_barrier
	s_waitcnt lgkmcnt(0)
	v_mfma_f32_16x16x32_bf16 v[60:63], v[152:155], v[184:187], v[60:63]
	v_mfma_f32_16x16x32_bf16 v[56:59], v[160:163], v[184:187], v[56:59]
	v_mfma_f32_16x16x32_bf16 v[52:55], v[152:155], v[192:195], v[52:55]
	v_mfma_f32_16x16x32_bf16 v[44:47], v[160:163], v[192:195], v[44:47]
	v_mfma_f32_16x16x32_bf16 v[36:39], v[152:155], v[200:203], v[36:39]
	v_mfma_f32_16x16x32_bf16 v[28:31], v[160:163], v[200:203], v[28:31]
	v_mfma_f32_16x16x32_bf16 v[20:23], v[152:155], v[208:211], v[20:23]
	v_mfma_f32_16x16x32_bf16 v[12:15], v[160:163], v[208:211], v[12:15]
	v_mfma_f32_16x16x32_bf16 v[60:63], v[156:159], v[188:191], v[60:63]
	v_mfma_f32_16x16x32_bf16 v[56:59], v[164:167], v[188:191], v[56:59]
	v_mfma_f32_16x16x32_bf16 v[52:55], v[156:159], v[196:199], v[52:55]
	v_mfma_f32_16x16x32_bf16 v[44:47], v[164:167], v[196:199], v[44:47]
	v_mfma_f32_16x16x32_bf16 v[36:39], v[156:159], v[204:207], v[36:39]
	v_mfma_f32_16x16x32_bf16 v[28:31], v[164:167], v[204:207], v[28:31]
	v_mfma_f32_16x16x32_bf16 v[20:23], v[156:159], v[212:215], v[20:23]
	v_mfma_f32_16x16x32_bf16 v[12:15], v[164:167], v[212:215], v[12:15]
	v_mfma_f32_16x16x32_bf16 v[48:51], v[168:171], v[184:187], v[48:51]
	v_mfma_f32_16x16x32_bf16 v[40:43], v[176:179], v[184:187], v[40:43]
	v_mfma_f32_16x16x32_bf16 v[32:35], v[168:171], v[192:195], v[32:35]
	v_mfma_f32_16x16x32_bf16 v[24:27], v[176:179], v[192:195], v[24:27]
	v_mfma_f32_16x16x32_bf16 v[16:19], v[168:171], v[200:203], v[16:19]
	v_mfma_f32_16x16x32_bf16 v[8:11], v[176:179], v[200:203], v[8:11]
	v_mfma_f32_16x16x32_bf16 v[4:7], v[168:171], v[208:211], v[4:7]
	v_mfma_f32_16x16x32_bf16 v[0:3], v[176:179], v[208:211], v[0:3]
	v_mfma_f32_16x16x32_bf16 v[48:51], v[172:175], v[188:191], v[48:51]
	v_mfma_f32_16x16x32_bf16 v[40:43], v[180:183], v[188:191], v[40:43]
	v_mfma_f32_16x16x32_bf16 v[32:35], v[172:175], v[196:199], v[32:35]
	v_mfma_f32_16x16x32_bf16 v[24:27], v[180:183], v[196:199], v[24:27]
	v_mfma_f32_16x16x32_bf16 v[16:19], v[172:175], v[204:207], v[16:19]
	v_mfma_f32_16x16x32_bf16 v[8:11], v[180:183], v[204:207], v[8:11]
	v_mfma_f32_16x16x32_bf16 v[4:7], v[172:175], v[212:215], v[4:7]
	v_mfma_f32_16x16x32_bf16 v[0:3], v[180:183], v[212:215], v[0:3]
	s_barrier
	s_add_i32 s59, 0, 0x18000
	s_add_i32 s62, 0, 0x1c000
	v_add_u32_e32 v164, s59, v146
	v_add_u32_e32 v180, s62, v146
	ds_read_b128 v[152:155], v164
	ds_read_b128 v[156:159], v164 offset:1024
	ds_read_b128 v[160:163], v164 offset:2048
	ds_read_b128 v[164:167], v164 offset:3072
	ds_read_b128 v[168:171], v180
	ds_read_b128 v[172:175], v180 offset:1024
	ds_read_b128 v[176:179], v180 offset:2048
	ds_read_b128 v[180:183], v180 offset:3072
	s_add_u32 s26, s26, 0x80000
	s_addc_u32 s27, s27, 0
	s_mov_b32 m0, s34
	ds_read_b128 v[184:187], v151 offset:32768
	ds_read_b128 v[188:191], v151 offset:33792
	ds_read_b128 v[192:195], v151 offset:34816
	ds_read_b128 v[196:199], v151 offset:35840
	ds_read_b128 v[200:203], v151 offset:36864
	ds_read_b128 v[204:207], v151 offset:37888
	ds_read_b128 v[208:211], v151 offset:38912
	ds_read_b128 v[212:215], v151 offset:39936
	global_load_lds_dwordx4 v128, s[26:27]
	s_mov_b32 m0, s35
	s_nop 0
	global_load_lds_dwordx4 v132, s[26:27]
	s_waitcnt vmcnt(8)
	s_waitcnt lgkmcnt(0)
	s_barrier
	s_waitcnt lgkmcnt(0)
	v_mfma_f32_16x16x32_bf16 v[124:127], v[152:155], v[184:187], v[124:127]
	v_mfma_f32_16x16x32_bf16 v[120:123], v[160:163], v[184:187], v[120:123]
	v_mfma_f32_16x16x32_bf16 v[116:119], v[152:155], v[192:195], v[116:119]
	v_mfma_f32_16x16x32_bf16 v[108:111], v[160:163], v[192:195], v[108:111]
	v_mfma_f32_16x16x32_bf16 v[100:103], v[152:155], v[200:203], v[100:103]
	v_mfma_f32_16x16x32_bf16 v[92:95], v[160:163], v[200:203], v[92:95]
	v_mfma_f32_16x16x32_bf16 v[84:87], v[152:155], v[208:211], v[84:87]
	v_mfma_f32_16x16x32_bf16 v[76:79], v[160:163], v[208:211], v[76:79]
	v_mfma_f32_16x16x32_bf16 v[124:127], v[156:159], v[188:191], v[124:127]
	v_mfma_f32_16x16x32_bf16 v[120:123], v[164:167], v[188:191], v[120:123]
	v_mfma_f32_16x16x32_bf16 v[116:119], v[156:159], v[196:199], v[116:119]
	v_mfma_f32_16x16x32_bf16 v[108:111], v[164:167], v[196:199], v[108:111]
	v_mfma_f32_16x16x32_bf16 v[100:103], v[156:159], v[204:207], v[100:103]
	v_mfma_f32_16x16x32_bf16 v[92:95], v[164:167], v[204:207], v[92:95]
	v_mfma_f32_16x16x32_bf16 v[84:87], v[156:159], v[212:215], v[84:87]
	v_mfma_f32_16x16x32_bf16 v[76:79], v[164:167], v[212:215], v[76:79]
	v_mfma_f32_16x16x32_bf16 v[112:115], v[168:171], v[184:187], v[112:115]
	v_mfma_f32_16x16x32_bf16 v[104:107], v[176:179], v[184:187], v[104:107]
	v_mfma_f32_16x16x32_bf16 v[96:99], v[168:171], v[192:195], v[96:99]
	v_mfma_f32_16x16x32_bf16 v[88:91], v[176:179], v[192:195], v[88:91]
	v_mfma_f32_16x16x32_bf16 v[80:83], v[168:171], v[200:203], v[80:83]
	v_mfma_f32_16x16x32_bf16 v[72:75], v[176:179], v[200:203], v[72:75]
	v_mfma_f32_16x16x32_bf16 v[68:71], v[168:171], v[208:211], v[68:71]
	v_mfma_f32_16x16x32_bf16 v[64:67], v[176:179], v[208:211], v[64:67]
	v_mfma_f32_16x16x32_bf16 v[112:115], v[172:175], v[188:191], v[112:115]
	v_mfma_f32_16x16x32_bf16 v[104:107], v[180:183], v[188:191], v[104:107]
	v_mfma_f32_16x16x32_bf16 v[96:99], v[172:175], v[196:199], v[96:99]
	v_mfma_f32_16x16x32_bf16 v[88:91], v[180:183], v[196:199], v[88:91]
	v_mfma_f32_16x16x32_bf16 v[80:83], v[172:175], v[204:207], v[80:83]
	v_mfma_f32_16x16x32_bf16 v[72:75], v[180:183], v[204:207], v[72:75]
	v_mfma_f32_16x16x32_bf16 v[68:71], v[172:175], v[212:215], v[68:71]
	v_mfma_f32_16x16x32_bf16 v[64:67], v[180:183], v[212:215], v[64:67]
	s_barrier
	s_add_i32 s26, s59, s28
	s_mov_b32 m0, s26
	ds_read_b128 v[184:187], v151 offset:49152
	ds_read_b128 v[188:191], v151 offset:50176
	ds_read_b128 v[192:195], v151 offset:51200
	ds_read_b128 v[196:199], v151 offset:52224
	ds_read_b128 v[200:203], v151 offset:53248
	ds_read_b128 v[204:207], v151 offset:54272
	ds_read_b128 v[208:211], v151 offset:55296
	ds_read_b128 v[212:215], v151 offset:56320
	global_load_lds_dwordx4 v130, s[98:99]
	s_add_i32 m0, s26, 0x2000
	s_add_u32 s24, s24, 0x200080
	s_addc_u32 s25, s25, 0
	s_add_i32 s26, s62, s28
	global_load_lds_dwordx4 v134, s[98:99]
	s_mov_b32 m0, s26
	s_nop 0
	global_load_lds_dwordx4 v130, s[24:25]
	s_add_i32 m0, s26, 0x2000
	s_nop 0
	global_load_lds_dwordx4 v134, s[24:25]
	s_mov_b32 m0, s37
	s_nop 0
	global_load_lds_dwordx4 v128, s[100:101]
	s_mov_b32 m0, s38
	s_nop 0
	global_load_lds_dwordx4 v132, s[100:101]
	s_waitcnt vmcnt(8)
	s_waitcnt lgkmcnt(0)
	s_barrier
	s_waitcnt lgkmcnt(0)
	v_mfma_f32_16x16x32_bf16 v[60:63], v[152:155], v[184:187], v[60:63]
	v_mfma_f32_16x16x32_bf16 v[56:59], v[160:163], v[184:187], v[56:59]
	v_mfma_f32_16x16x32_bf16 v[52:55], v[152:155], v[192:195], v[52:55]
	v_mfma_f32_16x16x32_bf16 v[44:47], v[160:163], v[192:195], v[44:47]
	v_mfma_f32_16x16x32_bf16 v[36:39], v[152:155], v[200:203], v[36:39]
	v_mfma_f32_16x16x32_bf16 v[28:31], v[160:163], v[200:203], v[28:31]
	v_mfma_f32_16x16x32_bf16 v[20:23], v[152:155], v[208:211], v[20:23]
	v_mfma_f32_16x16x32_bf16 v[12:15], v[160:163], v[208:211], v[12:15]
	v_mfma_f32_16x16x32_bf16 v[60:63], v[156:159], v[188:191], v[60:63]
	v_mfma_f32_16x16x32_bf16 v[56:59], v[164:167], v[188:191], v[56:59]
	v_mfma_f32_16x16x32_bf16 v[52:55], v[156:159], v[196:199], v[52:55]
	v_mfma_f32_16x16x32_bf16 v[44:47], v[164:167], v[196:199], v[44:47]
	v_mfma_f32_16x16x32_bf16 v[36:39], v[156:159], v[204:207], v[36:39]
	v_mfma_f32_16x16x32_bf16 v[28:31], v[164:167], v[204:207], v[28:31]
	v_mfma_f32_16x16x32_bf16 v[20:23], v[156:159], v[212:215], v[20:23]
	v_mfma_f32_16x16x32_bf16 v[12:15], v[164:167], v[212:215], v[12:15]
	v_mfma_f32_16x16x32_bf16 v[48:51], v[168:171], v[184:187], v[48:51]
	v_mfma_f32_16x16x32_bf16 v[40:43], v[176:179], v[184:187], v[40:43]
	v_mfma_f32_16x16x32_bf16 v[32:35], v[168:171], v[192:195], v[32:35]
	v_mfma_f32_16x16x32_bf16 v[24:27], v[176:179], v[192:195], v[24:27]
	v_mfma_f32_16x16x32_bf16 v[16:19], v[168:171], v[200:203], v[16:19]
	v_mfma_f32_16x16x32_bf16 v[8:11], v[176:179], v[200:203], v[8:11]
	v_mfma_f32_16x16x32_bf16 v[4:7], v[168:171], v[208:211], v[4:7]
	v_mfma_f32_16x16x32_bf16 v[0:3], v[176:179], v[208:211], v[0:3]
	v_mfma_f32_16x16x32_bf16 v[48:51], v[172:175], v[188:191], v[48:51]
	v_mfma_f32_16x16x32_bf16 v[40:43], v[180:183], v[188:191], v[40:43]
	v_mfma_f32_16x16x32_bf16 v[32:35], v[172:175], v[196:199], v[32:35]
	v_mfma_f32_16x16x32_bf16 v[24:27], v[180:183], v[196:199], v[24:27]
	v_mfma_f32_16x16x32_bf16 v[16:19], v[172:175], v[204:207], v[16:19]
	v_mfma_f32_16x16x32_bf16 v[8:11], v[180:183], v[204:207], v[8:11]
	v_mfma_f32_16x16x32_bf16 v[4:7], v[172:175], v[212:215], v[4:7]
	v_mfma_f32_16x16x32_bf16 v[0:3], v[180:183], v[212:215], v[0:3]
	s_barrier
	s_add_i32 s58, s58, 2
	s_add_u32 s22, s22, 0x100
	s_addc_u32 s23, s23, 0
	s_add_u32 s56, s56, 0x100
	s_addc_u32 s57, s57, 0
	s_cmp_gt_u32 s58, 29
	s_cbranch_scc0 .LBB0_163
	s_setprio 0
	s_and_b64 vcc, exec, s[10:11]
	s_cbranch_vccz .LBB0_166
	s_barrier

.Lp2_noswap:
	s_add_u32 s30, s30, 0x100080
	s_addc_u32 s31, s31, 0
	s_add_u32 s75, s34, 0x100
	v_mov_b32_e32 v0, 0
	s_addc_u32 s78, s35, 0
	s_mov_b32 s79, -2
	v_mov_b32_e32 v1, v0
	v_mov_b32_e32 v2, v0
	v_mov_b32_e32 v3, v0
	v_mov_b32_e32 v4, v0
	v_mov_b32_e32 v5, v0
	v_mov_b32_e32 v6, v0
	v_mov_b32_e32 v7, v0
	v_mov_b32_e32 v16, v0
	v_mov_b32_e32 v17, v0
	v_mov_b32_e32 v18, v0
	v_mov_b32_e32 v19, v0
	v_mov_b32_e32 v20, v0
	v_mov_b32_e32 v21, v0
	v_mov_b32_e32 v22, v0
	v_mov_b32_e32 v23, v0
	v_mov_b32_e32 v32, v0
	v_mov_b32_e32 v33, v0
	v_mov_b32_e32 v34, v0
	v_mov_b32_e32 v35, v0
	v_mov_b32_e32 v36, v0
	v_mov_b32_e32 v37, v0
	v_mov_b32_e32 v38, v0
	v_mov_b32_e32 v39, v0
	v_mov_b32_e32 v48, v0
	v_mov_b32_e32 v49, v0
	v_mov_b32_e32 v50, v0
	v_mov_b32_e32 v51, v0
	v_mov_b32_e32 v52, v0
	v_mov_b32_e32 v53, v0
	v_mov_b32_e32 v54, v0
	v_mov_b32_e32 v55, v0
	v_mov_b32_e32 v8, v0
	v_mov_b32_e32 v9, v0
	v_mov_b32_e32 v10, v0
	v_mov_b32_e32 v11, v0
	v_mov_b32_e32 v12, v0
	v_mov_b32_e32 v13, v0
	v_mov_b32_e32 v14, v0
	v_mov_b32_e32 v15, v0
	v_mov_b32_e32 v24, v0
	v_mov_b32_e32 v25, v0
	v_mov_b32_e32 v26, v0
	v_mov_b32_e32 v27, v0
	v_mov_b32_e32 v28, v0
	v_mov_b32_e32 v29, v0
	v_mov_b32_e32 v30, v0
	v_mov_b32_e32 v31, v0
	v_mov_b32_e32 v40, v0
	v_mov_b32_e32 v41, v0
	v_mov_b32_e32 v42, v0
	v_mov_b32_e32 v43, v0
	v_mov_b32_e32 v44, v0
	v_mov_b32_e32 v45, v0
	v_mov_b32_e32 v46, v0
	v_mov_b32_e32 v47, v0
	v_mov_b32_e32 v56, v0
	v_mov_b32_e32 v57, v0
	v_mov_b32_e32 v58, v0
	v_mov_b32_e32 v59, v0
	v_mov_b32_e32 v60, v0
	v_mov_b32_e32 v61, v0
	v_mov_b32_e32 v62, v0
	v_mov_b32_e32 v63, v0
	v_mov_b32_e32 v64, v0
	v_mov_b32_e32 v65, v0
	v_mov_b32_e32 v66, v0
	v_mov_b32_e32 v67, v0
	v_mov_b32_e32 v68, v0
	v_mov_b32_e32 v69, v0
	v_mov_b32_e32 v70, v0
	v_mov_b32_e32 v71, v0
	v_mov_b32_e32 v80, v0
	v_mov_b32_e32 v81, v0
	v_mov_b32_e32 v82, v0
	v_mov_b32_e32 v83, v0
	v_mov_b32_e32 v84, v0
	v_mov_b32_e32 v85, v0
	v_mov_b32_e32 v86, v0
	v_mov_b32_e32 v87, v0
	v_mov_b32_e32 v88, v0
	v_mov_b32_e32 v89, v0
	v_mov_b32_e32 v90, v0
	v_mov_b32_e32 v91, v0
	v_mov_b32_e32 v92, v0
	v_mov_b32_e32 v93, v0
	v_mov_b32_e32 v94, v0
	v_mov_b32_e32 v95, v0
	v_mov_b32_e32 v100, v0
	v_mov_b32_e32 v101, v0
	v_mov_b32_e32 v102, v0
	v_mov_b32_e32 v103, v0
	v_mov_b32_e32 v108, v0
	v_mov_b32_e32 v109, v0
	v_mov_b32_e32 v110, v0
	v_mov_b32_e32 v111, v0
	v_mov_b32_e32 v72, v0
	v_mov_b32_e32 v73, v0
	v_mov_b32_e32 v74, v0
	v_mov_b32_e32 v75, v0
	v_mov_b32_e32 v76, v0
	v_mov_b32_e32 v77, v0
	v_mov_b32_e32 v78, v0
	v_mov_b32_e32 v79, v0
	v_mov_b32_e32 v96, v0
	v_mov_b32_e32 v97, v0
	v_mov_b32_e32 v98, v0
	v_mov_b32_e32 v99, v0
	v_mov_b32_e32 v104, v0
	v_mov_b32_e32 v105, v0
	v_mov_b32_e32 v106, v0
	v_mov_b32_e32 v107, v0
	v_mov_b32_e32 v112, v0
	v_mov_b32_e32 v113, v0
	v_mov_b32_e32 v114, v0
	v_mov_b32_e32 v115, v0
	v_mov_b32_e32 v116, v0
	v_mov_b32_e32 v117, v0
	v_mov_b32_e32 v118, v0
	v_mov_b32_e32 v119, v0
	v_mov_b32_e32 v120, v0
	v_mov_b32_e32 v121, v0
	v_mov_b32_e32 v122, v0
	v_mov_b32_e32 v123, v0
	v_mov_b32_e32 v124, v0
	v_mov_b32_e32 v125, v0
	v_mov_b32_e32 v126, v0
	v_mov_b32_e32 v127, v0
	s_cmp_lt_u32 s89, 4
	s_cbranch_scc1 .Lprio_188
	s_setprio 1
.Lprio_188:
.LBB0_188:
	ds_read_b128 v[154:157], v149
	ds_read_b128 v[158:161], v149 offset:1024
	ds_read_b128 v[162:165], v149 offset:2048
	ds_read_b128 v[166:169], v149 offset:3072
	ds_read_b128 v[170:173], v150
	ds_read_b128 v[174:177], v150 offset:1024
	ds_read_b128 v[178:181], v150 offset:2048
	ds_read_b128 v[182:185], v150 offset:3072
	s_add_u32 s34, s30, 0xfff00080
	s_addc_u32 s35, s31, -1
	s_cmp_eq_u32 s79, 60
	s_cselect_b32 s37, s23, s35
	s_cselect_b32 s36, s73, s34
	s_cselect_b32 s35, s21, s78
	s_cselect_b32 s34, s74, s75
	s_add_u32 s98, s34, s10
	s_addc_u32 s99, s35, s11
	s_add_u32 s100, s36, s10
	s_addc_u32 s101, s37, s11
	s_add_i32 m0, s49, 0xc000
	ds_read_b128 v[186:189], v151
	ds_read_b128 v[190:193], v151 offset:1024
	ds_read_b128 v[194:197], v151 offset:2048
	ds_read_b128 v[198:201], v151 offset:3072
	ds_read_b128 v[202:205], v151 offset:4096
	ds_read_b128 v[206:209], v151 offset:5120
	ds_read_b128 v[210:213], v151 offset:6144
	ds_read_b128 v[214:217], v151 offset:7168
	global_load_lds_dwordx4 v136, s[30:31]
	s_add_i32 m0, s49, 0xe000
	s_nop 0
	global_load_lds_dwordx4 v138, s[30:31]
	s_waitcnt vmcnt(8)
	s_waitcnt lgkmcnt(0)
	s_barrier
	s_waitcnt lgkmcnt(0)
	v_mfma_f32_16x16x32_bf16 v[124:127], v[154:157], v[186:189], v[124:127]
	v_mfma_f32_16x16x32_bf16 v[120:123], v[162:165], v[186:189], v[120:123]
	v_mfma_f32_16x16x32_bf16 v[116:119], v[154:157], v[194:197], v[116:119]
	v_mfma_f32_16x16x32_bf16 v[112:115], v[162:165], v[194:197], v[112:115]
	v_mfma_f32_16x16x32_bf16 v[104:107], v[154:157], v[202:205], v[104:107]
	v_mfma_f32_16x16x32_bf16 v[96:99], v[162:165], v[202:205], v[96:99]
	v_mfma_f32_16x16x32_bf16 v[76:79], v[154:157], v[210:213], v[76:79]
	v_mfma_f32_16x16x32_bf16 v[72:75], v[162:165], v[210:213], v[72:75]
	v_mfma_f32_16x16x32_bf16 v[124:127], v[158:161], v[190:193], v[124:127]
	v_mfma_f32_16x16x32_bf16 v[120:123], v[166:169], v[190:193], v[120:123]
	v_mfma_f32_16x16x32_bf16 v[116:119], v[158:161], v[198:201], v[116:119]
	v_mfma_f32_16x16x32_bf16 v[112:115], v[166:169], v[198:201], v[112:115]
	v_mfma_f32_16x16x32_bf16 v[104:107], v[158:161], v[206:209], v[104:107]
	v_mfma_f32_16x16x32_bf16 v[96:99], v[166:169], v[206:209], v[96:99]
	v_mfma_f32_16x16x32_bf16 v[76:79], v[158:161], v[214:217], v[76:79]
	v_mfma_f32_16x16x32_bf16 v[72:75], v[166:169], v[214:217], v[72:75]
	v_mfma_f32_16x16x32_bf16 v[108:111], v[170:173], v[186:189], v[108:111]
	v_mfma_f32_16x16x32_bf16 v[100:103], v[178:181], v[186:189], v[100:103]
	v_mfma_f32_16x16x32_bf16 v[92:95], v[170:173], v[194:197], v[92:95]
	v_mfma_f32_16x16x32_bf16 v[88:91], v[178:181], v[194:197], v[88:91]
	v_mfma_f32_16x16x32_bf16 v[84:87], v[170:173], v[202:205], v[84:87]
	v_mfma_f32_16x16x32_bf16 v[80:83], v[178:181], v[202:205], v[80:83]
	v_mfma_f32_16x16x32_bf16 v[68:71], v[170:173], v[210:213], v[68:71]
	v_mfma_f32_16x16x32_bf16 v[64:67], v[178:181], v[210:213], v[64:67]
	v_mfma_f32_16x16x32_bf16 v[108:111], v[174:177], v[190:193], v[108:111]
	v_mfma_f32_16x16x32_bf16 v[100:103], v[182:185], v[190:193], v[100:103]
	v_mfma_f32_16x16x32_bf16 v[92:95], v[174:177], v[198:201], v[92:95]
	v_mfma_f32_16x16x32_bf16 v[88:91], v[182:185], v[198:201], v[88:91]
	v_mfma_f32_16x16x32_bf16 v[84:87], v[174:177], v[206:209], v[84:87]
	v_mfma_f32_16x16x32_bf16 v[80:83], v[182:185], v[206:209], v[80:83]
	v_mfma_f32_16x16x32_bf16 v[68:71], v[174:177], v[214:217], v[68:71]
	v_mfma_f32_16x16x32_bf16 v[64:67], v[182:185], v[214:217], v[64:67]
	s_barrier
	s_add_i32 s80, s63, s38
	s_mov_b32 m0, s80
	ds_read_b128 v[186:189], v151 offset:16384
	ds_read_b128 v[190:193], v151 offset:17408
	ds_read_b128 v[194:197], v151 offset:18432
	ds_read_b128 v[198:201], v151 offset:19456
	ds_read_b128 v[202:205], v151 offset:20480
	ds_read_b128 v[206:209], v151 offset:21504
	ds_read_b128 v[210:213], v151 offset:22528
	ds_read_b128 v[214:217], v151 offset:23552
	global_load_lds_dwordx4 v130, s[34:35]
	s_add_i32 m0, s80, 0x2000
	s_add_u32 s80, s34, 0x100000
	s_addc_u32 s81, s35, 0
	s_add_i32 s82, s68, s38
	global_load_lds_dwordx4 v134, s[34:35]
	s_mov_b32 m0, s82
	s_nop 0
	global_load_lds_dwordx4 v130, s[80:81]
	s_add_i32 m0, s82, 0x2000
	s_nop 0
	global_load_lds_dwordx4 v134, s[80:81]
	s_mov_b32 m0, s49
	s_nop 0
	global_load_lds_dwordx4 v128, s[36:37]
	s_mov_b32 m0, s54
	s_nop 0
	global_load_lds_dwordx4 v132, s[36:37]
	s_waitcnt vmcnt(8)
	s_waitcnt lgkmcnt(0)
	s_barrier
	s_waitcnt lgkmcnt(0)
	v_mfma_f32_16x16x32_bf16 v[60:63], v[154:157], v[186:189], v[60:63]
	v_mfma_f32_16x16x32_bf16 v[56:59], v[162:165], v[186:189], v[56:59]
	v_mfma_f32_16x16x32_bf16 v[44:47], v[154:157], v[194:197], v[44:47]
	v_mfma_f32_16x16x32_bf16 v[40:43], v[162:165], v[194:197], v[40:43]
	v_mfma_f32_16x16x32_bf16 v[28:31], v[154:157], v[202:205], v[28:31]
	v_mfma_f32_16x16x32_bf16 v[24:27], v[162:165], v[202:205], v[24:27]
	v_mfma_f32_16x16x32_bf16 v[12:15], v[154:157], v[210:213], v[12:15]
	v_mfma_f32_16x16x32_bf16 v[8:11], v[162:165], v[210:213], v[8:11]
	v_mfma_f32_16x16x32_bf16 v[60:63], v[158:161], v[190:193], v[60:63]
	v_mfma_f32_16x16x32_bf16 v[56:59], v[166:169], v[190:193], v[56:59]
	v_mfma_f32_16x16x32_bf16 v[44:47], v[158:161], v[198:201], v[44:47]
	v_mfma_f32_16x16x32_bf16 v[40:43], v[166:169], v[198:201], v[40:43]
	v_mfma_f32_16x16x32_bf16 v[28:31], v[158:161], v[206:209], v[28:31]
	v_mfma_f32_16x16x32_bf16 v[24:27], v[166:169], v[206:209], v[24:27]
	v_mfma_f32_16x16x32_bf16 v[12:15], v[158:161], v[214:217], v[12:15]
	v_mfma_f32_16x16x32_bf16 v[8:11], v[166:169], v[214:217], v[8:11]
	v_mfma_f32_16x16x32_bf16 v[52:55], v[170:173], v[186:189], v[52:55]
	v_mfma_f32_16x16x32_bf16 v[48:51], v[178:181], v[186:189], v[48:51]
	v_mfma_f32_16x16x32_bf16 v[36:39], v[170:173], v[194:197], v[36:39]
	v_mfma_f32_16x16x32_bf16 v[32:35], v[178:181], v[194:197], v[32:35]
	v_mfma_f32_16x16x32_bf16 v[20:23], v[170:173], v[202:205], v[20:23]
	v_mfma_f32_16x16x32_bf16 v[16:19], v[178:181], v[202:205], v[16:19]
	v_mfma_f32_16x16x32_bf16 v[4:7], v[170:173], v[210:213], v[4:7]
	v_mfma_f32_16x16x32_bf16 v[0:3], v[178:181], v[210:213], v[0:3]
	v_mfma_f32_16x16x32_bf16 v[52:55], v[174:177], v[190:193], v[52:55]
	v_mfma_f32_16x16x32_bf16 v[48:51], v[182:185], v[190:193], v[48:51]
	v_mfma_f32_16x16x32_bf16 v[36:39], v[174:177], v[198:201], v[36:39]
	v_mfma_f32_16x16x32_bf16 v[32:35], v[182:185], v[198:201], v[32:35]
	v_mfma_f32_16x16x32_bf16 v[20:23], v[174:177], v[206:209], v[20:23]
	v_mfma_f32_16x16x32_bf16 v[16:19], v[182:185], v[206:209], v[16:19]
	v_mfma_f32_16x16x32_bf16 v[4:7], v[174:177], v[214:217], v[4:7]
	v_mfma_f32_16x16x32_bf16 v[0:3], v[182:185], v[214:217], v[0:3]
	s_barrier
	s_add_i32 s80, 0, 0x18000
	s_add_i32 s81, 0, 0x1c000
	v_add_u32_e32 v166, s80, v147
	v_add_u32_e32 v182, s81, v147
	ds_read_b128 v[154:157], v166
	ds_read_b128 v[158:161], v166 offset:1024
	ds_read_b128 v[162:165], v166 offset:2048
	ds_read_b128 v[166:169], v166 offset:3072
	ds_read_b128 v[170:173], v182
	ds_read_b128 v[174:177], v182 offset:1024
	ds_read_b128 v[178:181], v182 offset:2048
	ds_read_b128 v[182:185], v182 offset:3072
	s_add_u32 s36, s36, 0x100000
	s_addc_u32 s37, s37, 0
	s_mov_b32 m0, s55
	ds_read_b128 v[186:189], v151 offset:32768
	ds_read_b128 v[190:193], v151 offset:33792
	ds_read_b128 v[194:197], v151 offset:34816
	ds_read_b128 v[198:201], v151 offset:35840
	ds_read_b128 v[202:205], v151 offset:36864
	ds_read_b128 v[206:209], v151 offset:37888
	ds_read_b128 v[210:213], v151 offset:38912
	ds_read_b128 v[214:217], v151 offset:39936
	global_load_lds_dwordx4 v128, s[36:37]
	s_mov_b32 m0, s56
	s_nop 0
	global_load_lds_dwordx4 v132, s[36:37]
	s_waitcnt vmcnt(8)
	s_waitcnt lgkmcnt(0)
	s_barrier
	s_waitcnt lgkmcnt(0)
	v_mfma_f32_16x16x32_bf16 v[124:127], v[154:157], v[186:189], v[124:127]
	v_mfma_f32_16x16x32_bf16 v[120:123], v[162:165], v[186:189], v[120:123]
	v_mfma_f32_16x16x32_bf16 v[116:119], v[154:157], v[194:197], v[116:119]
	v_mfma_f32_16x16x32_bf16 v[112:115], v[162:165], v[194:197], v[112:115]
	v_mfma_f32_16x16x32_bf16 v[104:107], v[154:157], v[202:205], v[104:107]
	v_mfma_f32_16x16x32_bf16 v[96:99], v[162:165], v[202:205], v[96:99]
	v_mfma_f32_16x16x32_bf16 v[76:79], v[154:157], v[210:213], v[76:79]
	v_mfma_f32_16x16x32_bf16 v[72:75], v[162:165], v[210:213], v[72:75]
	v_mfma_f32_16x16x32_bf16 v[124:127], v[158:161], v[190:193], v[124:127]
	v_mfma_f32_16x16x32_bf16 v[120:123], v[166:169], v[190:193], v[120:123]
	v_mfma_f32_16x16x32_bf16 v[116:119], v[158:161], v[198:201], v[116:119]
	v_mfma_f32_16x16x32_bf16 v[112:115], v[166:169], v[198:201], v[112:115]
	v_mfma_f32_16x16x32_bf16 v[104:107], v[158:161], v[206:209], v[104:107]
	v_mfma_f32_16x16x32_bf16 v[96:99], v[166:169], v[206:209], v[96:99]
	v_mfma_f32_16x16x32_bf16 v[76:79], v[158:161], v[214:217], v[76:79]
	v_mfma_f32_16x16x32_bf16 v[72:75], v[166:169], v[214:217], v[72:75]
	v_mfma_f32_16x16x32_bf16 v[108:111], v[170:173], v[186:189], v[108:111]
	v_mfma_f32_16x16x32_bf16 v[100:103], v[178:181], v[186:189], v[100:103]
	v_mfma_f32_16x16x32_bf16 v[92:95], v[170:173], v[194:197], v[92:95]
	v_mfma_f32_16x16x32_bf16 v[88:91], v[178:181], v[194:197], v[88:91]
	v_mfma_f32_16x16x32_bf16 v[84:87], v[170:173], v[202:205], v[84:87]
	v_mfma_f32_16x16x32_bf16 v[80:83], v[178:181], v[202:205], v[80:83]
	v_mfma_f32_16x16x32_bf16 v[68:71], v[170:173], v[210:213], v[68:71]
	v_mfma_f32_16x16x32_bf16 v[64:67], v[178:181], v[210:213], v[64:67]
	v_mfma_f32_16x16x32_bf16 v[108:111], v[174:177], v[190:193], v[108:111]
	v_mfma_f32_16x16x32_bf16 v[100:103], v[182:185], v[190:193], v[100:103]
	v_mfma_f32_16x16x32_bf16 v[92:95], v[174:177], v[198:201], v[92:95]
	v_mfma_f32_16x16x32_bf16 v[88:91], v[182:185], v[198:201], v[88:91]
	v_mfma_f32_16x16x32_bf16 v[84:87], v[174:177], v[206:209], v[84:87]
	v_mfma_f32_16x16x32_bf16 v[80:83], v[182:185], v[206:209], v[80:83]
	v_mfma_f32_16x16x32_bf16 v[68:71], v[174:177], v[214:217], v[68:71]
	v_mfma_f32_16x16x32_bf16 v[64:67], v[182:185], v[214:217], v[64:67]
	s_barrier
	s_add_i32 s36, s80, s38
	s_mov_b32 m0, s36
	ds_read_b128 v[186:189], v151 offset:49152
	ds_read_b128 v[190:193], v151 offset:50176
	ds_read_b128 v[194:197], v151 offset:51200
	ds_read_b128 v[198:201], v151 offset:52224
	ds_read_b128 v[202:205], v151 offset:53248
	ds_read_b128 v[206:209], v151 offset:54272
	ds_read_b128 v[210:213], v151 offset:55296
	ds_read_b128 v[214:217], v151 offset:56320
	global_load_lds_dwordx4 v130, s[98:99]
	s_add_i32 m0, s36, 0x2000
	s_add_u32 s34, s34, 0x100080
	s_addc_u32 s35, s35, 0
	s_add_i32 s36, s81, s38
	global_load_lds_dwordx4 v134, s[98:99]
	s_mov_b32 m0, s36
	s_nop 0
	global_load_lds_dwordx4 v130, s[34:35]
	s_add_i32 m0, s36, 0x2000
	s_nop 0
	global_load_lds_dwordx4 v134, s[34:35]
	s_mov_b32 m0, s58
	s_nop 0
	global_load_lds_dwordx4 v128, s[100:101]
	s_mov_b32 m0, s59
	s_nop 0
	global_load_lds_dwordx4 v132, s[100:101]
	s_waitcnt vmcnt(8)
	s_waitcnt lgkmcnt(0)
	s_barrier
	s_waitcnt lgkmcnt(0)
	v_mfma_f32_16x16x32_bf16 v[60:63], v[154:157], v[186:189], v[60:63]
	v_mfma_f32_16x16x32_bf16 v[56:59], v[162:165], v[186:189], v[56:59]
	v_mfma_f32_16x16x32_bf16 v[44:47], v[154:157], v[194:197], v[44:47]
	v_mfma_f32_16x16x32_bf16 v[40:43], v[162:165], v[194:197], v[40:43]
	v_mfma_f32_16x16x32_bf16 v[28:31], v[154:157], v[202:205], v[28:31]
	v_mfma_f32_16x16x32_bf16 v[24:27], v[162:165], v[202:205], v[24:27]
	v_mfma_f32_16x16x32_bf16 v[12:15], v[154:157], v[210:213], v[12:15]
	v_mfma_f32_16x16x32_bf16 v[8:11], v[162:165], v[210:213], v[8:11]
	v_mfma_f32_16x16x32_bf16 v[60:63], v[158:161], v[190:193], v[60:63]
	v_mfma_f32_16x16x32_bf16 v[56:59], v[166:169], v[190:193], v[56:59]
	v_mfma_f32_16x16x32_bf16 v[44:47], v[158:161], v[198:201], v[44:47]
	v_mfma_f32_16x16x32_bf16 v[40:43], v[166:169], v[198:201], v[40:43]
	v_mfma_f32_16x16x32_bf16 v[28:31], v[158:161], v[206:209], v[28:31]
	v_mfma_f32_16x16x32_bf16 v[24:27], v[166:169], v[206:209], v[24:27]
	v_mfma_f32_16x16x32_bf16 v[12:15], v[158:161], v[214:217], v[12:15]
	v_mfma_f32_16x16x32_bf16 v[8:11], v[166:169], v[214:217], v[8:11]
	v_mfma_f32_16x16x32_bf16 v[52:55], v[170:173], v[186:189], v[52:55]
	v_mfma_f32_16x16x32_bf16 v[48:51], v[178:181], v[186:189], v[48:51]
	v_mfma_f32_16x16x32_bf16 v[36:39], v[170:173], v[194:197], v[36:39]
	v_mfma_f32_16x16x32_bf16 v[32:35], v[178:181], v[194:197], v[32:35]
	v_mfma_f32_16x16x32_bf16 v[20:23], v[170:173], v[202:205], v[20:23]
	v_mfma_f32_16x16x32_bf16 v[16:19], v[178:181], v[202:205], v[16:19]
	v_mfma_f32_16x16x32_bf16 v[4:7], v[170:173], v[210:213], v[4:7]
	v_mfma_f32_16x16x32_bf16 v[0:3], v[178:181], v[210:213], v[0:3]
	v_mfma_f32_16x16x32_bf16 v[52:55], v[174:177], v[190:193], v[52:55]
	v_mfma_f32_16x16x32_bf16 v[48:51], v[182:185], v[190:193], v[48:51]
	v_mfma_f32_16x16x32_bf16 v[36:39], v[174:177], v[198:201], v[36:39]
	v_mfma_f32_16x16x32_bf16 v[32:35], v[182:185], v[198:201], v[32:35]
	v_mfma_f32_16x16x32_bf16 v[20:23], v[174:177], v[206:209], v[20:23]
	v_mfma_f32_16x16x32_bf16 v[16:19], v[182:185], v[206:209], v[16:19]
	v_mfma_f32_16x16x32_bf16 v[4:7], v[174:177], v[214:217], v[4:7]
	v_mfma_f32_16x16x32_bf16 v[0:3], v[182:185], v[214:217], v[0:3]
	s_barrier
	s_add_i32 s79, s79, 2
	s_add_u32 s30, s30, 0x100
	s_addc_u32 s31, s31, 0
	s_add_u32 s75, s75, 0x100
	s_addc_u32 s78, s78, 0
	s_cmp_gt_u32 s79, 61
	s_cbranch_scc0 .LBB0_188
	s_setprio 0
	s_and_b64 vcc, exec, s[12:13]
	s_cbranch_vccz .LBB0_191
	s_barrier

.LBB0_430:
	s_ashr_i32 s15, s14, 31
	s_lshl_b64 s[16:17], s[14:15], 21
	s_add_u32 s16, s56, s16
	s_addc_u32 s17, s57, s17
	s_and_b64 s[18:19], s[4:5], exec
	s_cselect_b32 s15, s17, s27
	s_cselect_b32 s21, s16, s26
	s_ashr_i32 s13, s12, 31
	s_lshl_b64 s[18:19], s[12:13], 21
	v_readlane_b32 s30, v254, 5
	v_readlane_b32 s31, v254, 6
	s_add_u32 s18, s30, s18
	s_addc_u32 s19, s31, s19
	s_and_b64 s[30:31], s[4:5], exec
	s_cselect_b32 s13, s19, s29
	s_cselect_b32 s52, s18, s28
	s_add_u32 s26, s26, 0x100080
	s_addc_u32 s27, s27, 0
	s_add_u32 s53, s28, 0x100
	v_mov_b32_e32 v0, 0
	s_addc_u32 s54, s29, 0
	s_mov_b32 s55, -2
	s_waitcnt lgkmcnt(0)
	v_mov_b32_e32 v1, v0
	v_mov_b32_e32 v2, v0
	v_mov_b32_e32 v3, v0
	v_mov_b32_e32 v4, v0
	v_mov_b32_e32 v5, v0
	v_mov_b32_e32 v6, v0
	v_mov_b32_e32 v7, v0
	v_mov_b32_e32 v16, v0
	v_mov_b32_e32 v17, v0
	v_mov_b32_e32 v18, v0
	v_mov_b32_e32 v19, v0
	v_mov_b32_e32 v20, v0
	v_mov_b32_e32 v21, v0
	v_mov_b32_e32 v22, v0
	v_mov_b32_e32 v23, v0
	v_mov_b32_e32 v32, v0
	v_mov_b32_e32 v33, v0
	v_mov_b32_e32 v34, v0
	v_mov_b32_e32 v35, v0
	v_mov_b32_e32 v36, v0
	v_mov_b32_e32 v37, v0
	v_mov_b32_e32 v38, v0
	v_mov_b32_e32 v39, v0
	v_mov_b32_e32 v48, v0
	v_mov_b32_e32 v49, v0
	v_mov_b32_e32 v50, v0
	v_mov_b32_e32 v51, v0
	v_mov_b32_e32 v52, v0
	v_mov_b32_e32 v53, v0
	v_mov_b32_e32 v54, v0
	v_mov_b32_e32 v55, v0
	v_mov_b32_e32 v8, v0
	v_mov_b32_e32 v9, v0
	v_mov_b32_e32 v10, v0
	v_mov_b32_e32 v11, v0
	v_mov_b32_e32 v12, v0
	v_mov_b32_e32 v13, v0
	v_mov_b32_e32 v14, v0
	v_mov_b32_e32 v15, v0
	v_mov_b32_e32 v24, v0
	v_mov_b32_e32 v25, v0
	v_mov_b32_e32 v26, v0
	v_mov_b32_e32 v27, v0
	v_mov_b32_e32 v28, v0
	v_mov_b32_e32 v29, v0
	v_mov_b32_e32 v30, v0
	v_mov_b32_e32 v31, v0
	v_mov_b32_e32 v40, v0
	v_mov_b32_e32 v41, v0
	v_mov_b32_e32 v42, v0
	v_mov_b32_e32 v43, v0
	v_mov_b32_e32 v44, v0
	v_mov_b32_e32 v45, v0
	v_mov_b32_e32 v46, v0
	v_mov_b32_e32 v47, v0
	v_mov_b32_e32 v56, v0
	v_mov_b32_e32 v57, v0
	v_mov_b32_e32 v58, v0
	v_mov_b32_e32 v59, v0
	v_mov_b32_e32 v60, v0
	v_mov_b32_e32 v61, v0
	v_mov_b32_e32 v62, v0
	v_mov_b32_e32 v63, v0
	v_mov_b32_e32 v64, v0
	v_mov_b32_e32 v65, v0
	v_mov_b32_e32 v66, v0
	v_mov_b32_e32 v67, v0
	v_mov_b32_e32 v68, v0
	v_mov_b32_e32 v69, v0
	v_mov_b32_e32 v70, v0
	v_mov_b32_e32 v71, v0
	v_mov_b32_e32 v80, v0
	v_mov_b32_e32 v81, v0
	v_mov_b32_e32 v82, v0
	v_mov_b32_e32 v83, v0
	v_mov_b32_e32 v84, v0
	v_mov_b32_e32 v85, v0
	v_mov_b32_e32 v86, v0
	v_mov_b32_e32 v87, v0
	v_mov_b32_e32 v96, v0
	v_mov_b32_e32 v97, v0
	v_mov_b32_e32 v98, v0
	v_mov_b32_e32 v99, v0
	v_mov_b32_e32 v100, v0
	v_mov_b32_e32 v101, v0
	v_mov_b32_e32 v102, v0
	v_mov_b32_e32 v103, v0
	v_mov_b32_e32 v112, v0
	v_mov_b32_e32 v113, v0
	v_mov_b32_e32 v114, v0
	v_mov_b32_e32 v115, v0
	v_mov_b32_e32 v116, v0
	v_mov_b32_e32 v117, v0
	v_mov_b32_e32 v118, v0
	v_mov_b32_e32 v119, v0
	v_mov_b32_e32 v72, v0
	v_mov_b32_e32 v73, v0
	v_mov_b32_e32 v74, v0
	v_mov_b32_e32 v75, v0
	v_mov_b32_e32 v76, v0
	v_mov_b32_e32 v77, v0
	v_mov_b32_e32 v78, v0
	v_mov_b32_e32 v79, v0
	v_mov_b32_e32 v88, v0
	v_mov_b32_e32 v89, v0
	v_mov_b32_e32 v90, v0
	v_mov_b32_e32 v91, v0
	v_mov_b32_e32 v92, v0
	v_mov_b32_e32 v93, v0
	v_mov_b32_e32 v94, v0
	v_mov_b32_e32 v95, v0
	v_mov_b32_e32 v104, v0
	v_mov_b32_e32 v105, v0
	v_mov_b32_e32 v106, v0
	v_mov_b32_e32 v107, v0
	v_mov_b32_e32 v108, v0
	v_mov_b32_e32 v109, v0
	v_mov_b32_e32 v110, v0
	v_mov_b32_e32 v111, v0
	v_mov_b32_e32 v120, v0
	v_mov_b32_e32 v121, v0
	v_mov_b32_e32 v122, v0
	v_mov_b32_e32 v123, v0
	v_mov_b32_e32 v124, v0
	v_mov_b32_e32 v125, v0
	v_mov_b32_e32 v126, v0
	v_mov_b32_e32 v127, v0
	s_cmp_lt_u32 s89, 4
	s_cbranch_scc1 .Lprio_431
	s_setprio 1
.Lprio_431:
.LBB0_431:
	ds_read_b128 v[128:131], v207
	ds_read_b128 v[132:135], v207 offset:1024
	ds_read_b128 v[136:139], v207 offset:2048
	ds_read_b128 v[140:143], v207 offset:3072
	ds_read_b128 v[144:147], v208
	ds_read_b128 v[148:151], v208 offset:1024
	ds_read_b128 v[152:155], v208 offset:2048
	ds_read_b128 v[156:159], v208 offset:3072
	s_add_u32 s28, s26, 0xfff00080
	s_addc_u32 s29, s27, -1
	s_cmp_eq_u32 s55, 60
	s_cselect_b32 s31, s15, s29
	s_cselect_b32 s30, s21, s28
	s_cselect_b32 s29, s13, s54
	s_cselect_b32 s28, s52, s53
	s_add_u32 s98, s28, s8
	s_addc_u32 s99, s29, s9
	s_add_u32 s100, s30, s8
	s_addc_u32 s101, s31, s9
	s_add_i32 m0, s23, 0xc000
	ds_read_b128 v[160:163], v209
	ds_read_b128 v[164:167], v209 offset:1024
	ds_read_b128 v[168:171], v209 offset:2048
	ds_read_b128 v[172:175], v209 offset:3072
	ds_read_b128 v[192:195], v209 offset:4096
	ds_read_b128 v[196:199], v209 offset:5120
	ds_read_b128 v[200:203], v209 offset:6144
	ds_read_b128 v[212:215], v209 offset:7168
	global_load_lds_dwordx4 v184, s[26:27]
	s_add_i32 m0, s23, 0xe000
	s_nop 0
	global_load_lds_dwordx4 v186, s[26:27]
	s_waitcnt vmcnt(8)
	s_waitcnt lgkmcnt(0)
	s_barrier
	s_waitcnt lgkmcnt(0)
	v_mfma_f32_16x16x32_bf16 v[124:127], v[128:131], v[160:163], v[124:127]
	v_mfma_f32_16x16x32_bf16 v[120:123], v[136:139], v[160:163], v[120:123]
	v_mfma_f32_16x16x32_bf16 v[108:111], v[128:131], v[168:171], v[108:111]
	v_mfma_f32_16x16x32_bf16 v[104:107], v[136:139], v[168:171], v[104:107]
	v_mfma_f32_16x16x32_bf16 v[92:95], v[128:131], v[192:195], v[92:95]
	v_mfma_f32_16x16x32_bf16 v[88:91], v[136:139], v[192:195], v[88:91]
	v_mfma_f32_16x16x32_bf16 v[76:79], v[128:131], v[200:203], v[76:79]
	v_mfma_f32_16x16x32_bf16 v[72:75], v[136:139], v[200:203], v[72:75]
	v_mfma_f32_16x16x32_bf16 v[124:127], v[132:135], v[164:167], v[124:127]
	v_mfma_f32_16x16x32_bf16 v[120:123], v[140:143], v[164:167], v[120:123]
	v_mfma_f32_16x16x32_bf16 v[108:111], v[132:135], v[172:175], v[108:111]
	v_mfma_f32_16x16x32_bf16 v[104:107], v[140:143], v[172:175], v[104:107]
	v_mfma_f32_16x16x32_bf16 v[92:95], v[132:135], v[196:199], v[92:95]
	v_mfma_f32_16x16x32_bf16 v[88:91], v[140:143], v[196:199], v[88:91]
	v_mfma_f32_16x16x32_bf16 v[76:79], v[132:135], v[212:215], v[76:79]
	v_mfma_f32_16x16x32_bf16 v[72:75], v[140:143], v[212:215], v[72:75]
	v_mfma_f32_16x16x32_bf16 v[116:119], v[144:147], v[160:163], v[116:119]
	v_mfma_f32_16x16x32_bf16 v[112:115], v[152:155], v[160:163], v[112:115]
	v_mfma_f32_16x16x32_bf16 v[100:103], v[144:147], v[168:171], v[100:103]
	v_mfma_f32_16x16x32_bf16 v[96:99], v[152:155], v[168:171], v[96:99]
	v_mfma_f32_16x16x32_bf16 v[84:87], v[144:147], v[192:195], v[84:87]
	v_mfma_f32_16x16x32_bf16 v[80:83], v[152:155], v[192:195], v[80:83]
	v_mfma_f32_16x16x32_bf16 v[68:71], v[144:147], v[200:203], v[68:71]
	v_mfma_f32_16x16x32_bf16 v[64:67], v[152:155], v[200:203], v[64:67]
	v_mfma_f32_16x16x32_bf16 v[116:119], v[148:151], v[164:167], v[116:119]
	v_mfma_f32_16x16x32_bf16 v[112:115], v[156:159], v[164:167], v[112:115]
	v_mfma_f32_16x16x32_bf16 v[100:103], v[148:151], v[172:175], v[100:103]
	v_mfma_f32_16x16x32_bf16 v[96:99], v[156:159], v[172:175], v[96:99]
	v_mfma_f32_16x16x32_bf16 v[84:87], v[148:151], v[196:199], v[84:87]
	v_mfma_f32_16x16x32_bf16 v[80:83], v[156:159], v[196:199], v[80:83]
	v_mfma_f32_16x16x32_bf16 v[68:71], v[148:151], v[212:215], v[68:71]
	v_mfma_f32_16x16x32_bf16 v[64:67], v[156:159], v[212:215], v[64:67]
	s_barrier
	s_add_i32 s58, s50, s3
	s_mov_b32 m0, s58
	ds_read_b128 v[160:163], v209 offset:16384
	ds_read_b128 v[164:167], v209 offset:17408
	ds_read_b128 v[168:171], v209 offset:18432
	ds_read_b128 v[172:175], v209 offset:19456
	ds_read_b128 v[192:195], v209 offset:20480
	ds_read_b128 v[196:199], v209 offset:21504
	ds_read_b128 v[200:203], v209 offset:22528
	ds_read_b128 v[212:215], v209 offset:23552
	global_load_lds_dwordx4 v178, s[28:29]
	s_add_i32 m0, s58, 0x2000
	s_add_u32 s58, s28, 0x100000
	s_addc_u32 s59, s29, 0
	s_add_i32 s62, s51, s3
	global_load_lds_dwordx4 v182, s[28:29]
	s_mov_b32 m0, s62
	s_nop 0
	global_load_lds_dwordx4 v178, s[58:59]
	s_add_i32 m0, s62, 0x2000
	s_nop 0
	global_load_lds_dwordx4 v182, s[58:59]
	s_mov_b32 m0, s23
	s_nop 0
	global_load_lds_dwordx4 v176, s[30:31]
	s_mov_b32 m0, s34
	s_nop 0
	global_load_lds_dwordx4 v180, s[30:31]
	s_waitcnt vmcnt(8)
	s_waitcnt lgkmcnt(0)
	s_barrier
	s_waitcnt lgkmcnt(0)
	v_mfma_f32_16x16x32_bf16 v[60:63], v[128:131], v[160:163], v[60:63]
	v_mfma_f32_16x16x32_bf16 v[56:59], v[136:139], v[160:163], v[56:59]
	v_mfma_f32_16x16x32_bf16 v[44:47], v[128:131], v[168:171], v[44:47]
	v_mfma_f32_16x16x32_bf16 v[40:43], v[136:139], v[168:171], v[40:43]
	v_mfma_f32_16x16x32_bf16 v[28:31], v[128:131], v[192:195], v[28:31]
	v_mfma_f32_16x16x32_bf16 v[24:27], v[136:139], v[192:195], v[24:27]
	v_mfma_f32_16x16x32_bf16 v[12:15], v[128:131], v[200:203], v[12:15]
	v_mfma_f32_16x16x32_bf16 v[8:11], v[136:139], v[200:203], v[8:11]
	v_mfma_f32_16x16x32_bf16 v[60:63], v[132:135], v[164:167], v[60:63]
	v_mfma_f32_16x16x32_bf16 v[56:59], v[140:143], v[164:167], v[56:59]
	v_mfma_f32_16x16x32_bf16 v[44:47], v[132:135], v[172:175], v[44:47]
	v_mfma_f32_16x16x32_bf16 v[40:43], v[140:143], v[172:175], v[40:43]
	v_mfma_f32_16x16x32_bf16 v[28:31], v[132:135], v[196:199], v[28:31]
	v_mfma_f32_16x16x32_bf16 v[24:27], v[140:143], v[196:199], v[24:27]
	v_mfma_f32_16x16x32_bf16 v[12:15], v[132:135], v[212:215], v[12:15]
	v_mfma_f32_16x16x32_bf16 v[8:11], v[140:143], v[212:215], v[8:11]
	v_mfma_f32_16x16x32_bf16 v[52:55], v[144:147], v[160:163], v[52:55]
	v_mfma_f32_16x16x32_bf16 v[48:51], v[152:155], v[160:163], v[48:51]
	v_mfma_f32_16x16x32_bf16 v[36:39], v[144:147], v[168:171], v[36:39]
	v_mfma_f32_16x16x32_bf16 v[32:35], v[152:155], v[168:171], v[32:35]
	v_mfma_f32_16x16x32_bf16 v[20:23], v[144:147], v[192:195], v[20:23]
	v_mfma_f32_16x16x32_bf16 v[16:19], v[152:155], v[192:195], v[16:19]
	v_mfma_f32_16x16x32_bf16 v[4:7], v[144:147], v[200:203], v[4:7]
	v_mfma_f32_16x16x32_bf16 v[0:3], v[152:155], v[200:203], v[0:3]
	v_mfma_f32_16x16x32_bf16 v[52:55], v[148:151], v[164:167], v[52:55]
	v_mfma_f32_16x16x32_bf16 v[48:51], v[156:159], v[164:167], v[48:51]
	v_mfma_f32_16x16x32_bf16 v[36:39], v[148:151], v[172:175], v[36:39]
	v_mfma_f32_16x16x32_bf16 v[32:35], v[156:159], v[172:175], v[32:35]
	v_mfma_f32_16x16x32_bf16 v[20:23], v[148:151], v[196:199], v[20:23]
	v_mfma_f32_16x16x32_bf16 v[16:19], v[156:159], v[196:199], v[16:19]
	v_mfma_f32_16x16x32_bf16 v[4:7], v[148:151], v[212:215], v[4:7]
	v_mfma_f32_16x16x32_bf16 v[0:3], v[156:159], v[212:215], v[0:3]
	s_barrier
	s_add_i32 s58, 0, 0x18000
	s_add_i32 s59, 0, 0x1c000
	v_add_u32_e32 v140, s58, v205
	v_add_u32_e32 v156, s59, v205
	ds_read_b128 v[128:131], v140
	ds_read_b128 v[132:135], v140 offset:1024
	ds_read_b128 v[136:139], v140 offset:2048
	ds_read_b128 v[140:143], v140 offset:3072
	ds_read_b128 v[144:147], v156
	ds_read_b128 v[148:151], v156 offset:1024
	ds_read_b128 v[152:155], v156 offset:2048
	ds_read_b128 v[156:159], v156 offset:3072
	s_add_u32 s30, s30, 0x100000
	s_addc_u32 s31, s31, 0
	s_mov_b32 m0, s35
	ds_read_b128 v[160:163], v209 offset:32768
	ds_read_b128 v[164:167], v209 offset:33792
	ds_read_b128 v[168:171], v209 offset:34816
	ds_read_b128 v[172:175], v209 offset:35840
	ds_read_b128 v[192:195], v209 offset:36864
	ds_read_b128 v[196:199], v209 offset:37888
	ds_read_b128 v[200:203], v209 offset:38912
	ds_read_b128 v[212:215], v209 offset:39936
	global_load_lds_dwordx4 v176, s[30:31]
	s_mov_b32 m0, s36
	s_nop 0
	global_load_lds_dwordx4 v180, s[30:31]
	s_waitcnt vmcnt(8)
	s_waitcnt lgkmcnt(0)
	s_barrier
	s_waitcnt lgkmcnt(0)
	v_mfma_f32_16x16x32_bf16 v[124:127], v[128:131], v[160:163], v[124:127]
	v_mfma_f32_16x16x32_bf16 v[120:123], v[136:139], v[160:163], v[120:123]
	v_mfma_f32_16x16x32_bf16 v[108:111], v[128:131], v[168:171], v[108:111]
	v_mfma_f32_16x16x32_bf16 v[104:107], v[136:139], v[168:171], v[104:107]
	v_mfma_f32_16x16x32_bf16 v[92:95], v[128:131], v[192:195], v[92:95]
	v_mfma_f32_16x16x32_bf16 v[88:91], v[136:139], v[192:195], v[88:91]
	v_mfma_f32_16x16x32_bf16 v[76:79], v[128:131], v[200:203], v[76:79]
	v_mfma_f32_16x16x32_bf16 v[72:75], v[136:139], v[200:203], v[72:75]
	v_mfma_f32_16x16x32_bf16 v[124:127], v[132:135], v[164:167], v[124:127]
	v_mfma_f32_16x16x32_bf16 v[120:123], v[140:143], v[164:167], v[120:123]
	v_mfma_f32_16x16x32_bf16 v[108:111], v[132:135], v[172:175], v[108:111]
	v_mfma_f32_16x16x32_bf16 v[104:107], v[140:143], v[172:175], v[104:107]
	v_mfma_f32_16x16x32_bf16 v[92:95], v[132:135], v[196:199], v[92:95]
	v_mfma_f32_16x16x32_bf16 v[88:91], v[140:143], v[196:199], v[88:91]
	v_mfma_f32_16x16x32_bf16 v[76:79], v[132:135], v[212:215], v[76:79]
	v_mfma_f32_16x16x32_bf16 v[72:75], v[140:143], v[212:215], v[72:75]
	v_mfma_f32_16x16x32_bf16 v[116:119], v[144:147], v[160:163], v[116:119]
	v_mfma_f32_16x16x32_bf16 v[112:115], v[152:155], v[160:163], v[112:115]
	v_mfma_f32_16x16x32_bf16 v[100:103], v[144:147], v[168:171], v[100:103]
	v_mfma_f32_16x16x32_bf16 v[96:99], v[152:155], v[168:171], v[96:99]
	v_mfma_f32_16x16x32_bf16 v[84:87], v[144:147], v[192:195], v[84:87]
	v_mfma_f32_16x16x32_bf16 v[80:83], v[152:155], v[192:195], v[80:83]
	v_mfma_f32_16x16x32_bf16 v[68:71], v[144:147], v[200:203], v[68:71]
	v_mfma_f32_16x16x32_bf16 v[64:67], v[152:155], v[200:203], v[64:67]
	v_mfma_f32_16x16x32_bf16 v[116:119], v[148:151], v[164:167], v[116:119]
	v_mfma_f32_16x16x32_bf16 v[112:115], v[156:159], v[164:167], v[112:115]
	v_mfma_f32_16x16x32_bf16 v[100:103], v[148:151], v[172:175], v[100:103]
	v_mfma_f32_16x16x32_bf16 v[96:99], v[156:159], v[172:175], v[96:99]
	v_mfma_f32_16x16x32_bf16 v[84:87], v[148:151], v[196:199], v[84:87]
	v_mfma_f32_16x16x32_bf16 v[80:83], v[156:159], v[196:199], v[80:83]
	v_mfma_f32_16x16x32_bf16 v[68:71], v[148:151], v[212:215], v[68:71]
	v_mfma_f32_16x16x32_bf16 v[64:67], v[156:159], v[212:215], v[64:67]
	s_barrier
	s_add_i32 s30, s58, s3
	s_mov_b32 m0, s30
	ds_read_b128 v[160:163], v209 offset:49152
	ds_read_b128 v[164:167], v209 offset:50176
	ds_read_b128 v[168:171], v209 offset:51200
	ds_read_b128 v[172:175], v209 offset:52224
	ds_read_b128 v[192:195], v209 offset:53248
	ds_read_b128 v[196:199], v209 offset:54272
	ds_read_b128 v[200:203], v209 offset:55296
	ds_read_b128 v[212:215], v209 offset:56320
	global_load_lds_dwordx4 v178, s[98:99]
	s_add_i32 m0, s30, 0x2000
	s_add_u32 s28, s28, 0x100080
	s_addc_u32 s29, s29, 0
	s_add_i32 s30, s59, s3
	global_load_lds_dwordx4 v182, s[98:99]
	s_mov_b32 m0, s30
	s_nop 0
	global_load_lds_dwordx4 v178, s[28:29]
	s_add_i32 m0, s30, 0x2000
	s_nop 0
	global_load_lds_dwordx4 v182, s[28:29]
	s_mov_b32 m0, s38
	s_nop 0
	global_load_lds_dwordx4 v176, s[100:101]
	s_mov_b32 m0, s39
	s_nop 0
	global_load_lds_dwordx4 v180, s[100:101]
	s_waitcnt vmcnt(8)
	s_waitcnt lgkmcnt(0)
	s_barrier
	s_waitcnt lgkmcnt(0)
	v_mfma_f32_16x16x32_bf16 v[60:63], v[128:131], v[160:163], v[60:63]
	v_mfma_f32_16x16x32_bf16 v[56:59], v[136:139], v[160:163], v[56:59]
	v_mfma_f32_16x16x32_bf16 v[44:47], v[128:131], v[168:171], v[44:47]
	v_mfma_f32_16x16x32_bf16 v[40:43], v[136:139], v[168:171], v[40:43]
	v_mfma_f32_16x16x32_bf16 v[28:31], v[128:131], v[192:195], v[28:31]
	v_mfma_f32_16x16x32_bf16 v[24:27], v[136:139], v[192:195], v[24:27]
	v_mfma_f32_16x16x32_bf16 v[12:15], v[128:131], v[200:203], v[12:15]
	v_mfma_f32_16x16x32_bf16 v[8:11], v[136:139], v[200:203], v[8:11]
	v_mfma_f32_16x16x32_bf16 v[60:63], v[132:135], v[164:167], v[60:63]
	v_mfma_f32_16x16x32_bf16 v[56:59], v[140:143], v[164:167], v[56:59]
	v_mfma_f32_16x16x32_bf16 v[44:47], v[132:135], v[172:175], v[44:47]
	v_mfma_f32_16x16x32_bf16 v[40:43], v[140:143], v[172:175], v[40:43]
	v_mfma_f32_16x16x32_bf16 v[28:31], v[132:135], v[196:199], v[28:31]
	v_mfma_f32_16x16x32_bf16 v[24:27], v[140:143], v[196:199], v[24:27]
	v_mfma_f32_16x16x32_bf16 v[12:15], v[132:135], v[212:215], v[12:15]
	v_mfma_f32_16x16x32_bf16 v[8:11], v[140:143], v[212:215], v[8:11]
	v_mfma_f32_16x16x32_bf16 v[52:55], v[144:147], v[160:163], v[52:55]
	v_mfma_f32_16x16x32_bf16 v[48:51], v[152:155], v[160:163], v[48:51]
	v_mfma_f32_16x16x32_bf16 v[36:39], v[144:147], v[168:171], v[36:39]
	v_mfma_f32_16x16x32_bf16 v[32:35], v[152:155], v[168:171], v[32:35]
	v_mfma_f32_16x16x32_bf16 v[20:23], v[144:147], v[192:195], v[20:23]
	v_mfma_f32_16x16x32_bf16 v[16:19], v[152:155], v[192:195], v[16:19]
	v_mfma_f32_16x16x32_bf16 v[4:7], v[144:147], v[200:203], v[4:7]
	v_mfma_f32_16x16x32_bf16 v[0:3], v[152:155], v[200:203], v[0:3]
	v_mfma_f32_16x16x32_bf16 v[52:55], v[148:151], v[164:167], v[52:55]
	v_mfma_f32_16x16x32_bf16 v[48:51], v[156:159], v[164:167], v[48:51]
	v_mfma_f32_16x16x32_bf16 v[36:39], v[148:151], v[172:175], v[36:39]
	v_mfma_f32_16x16x32_bf16 v[32:35], v[156:159], v[172:175], v[32:35]
	v_mfma_f32_16x16x32_bf16 v[20:23], v[148:151], v[196:199], v[20:23]
	v_mfma_f32_16x16x32_bf16 v[16:19], v[156:159], v[196:199], v[16:19]
	v_mfma_f32_16x16x32_bf16 v[4:7], v[148:151], v[212:215], v[4:7]
	v_mfma_f32_16x16x32_bf16 v[0:3], v[156:159], v[212:215], v[0:3]
	s_barrier
	s_add_i32 s55, s55, 2
	s_add_u32 s26, s26, 0x100
	s_addc_u32 s27, s27, 0
	s_add_u32 s53, s53, 0x100
	s_addc_u32 s54, s54, 0
	s_cmp_gt_u32 s55, 61
	s_cbranch_scc0 .LBB0_431
	s_setprio 0
	s_and_b64 vcc, exec, s[10:11]
	s_cbranch_vccz .LBB0_434
	s_barrier

.LBB0_527:
	s_ashr_i32 s47, s46, 31
	s_lshl_b64 s[50:51], s[46:47], 21
	s_add_u32 s50, s42, s50
	s_addc_u32 s51, s43, s51
	s_and_b64 s[52:53], s[18:19], exec
	s_cselect_b32 s47, s51, s21
	s_cselect_b32 s57, s50, s20
	s_ashr_i32 s41, s40, 31
	s_lshl_b64 s[52:53], s[40:41], 21
	s_add_u32 s52, s76, s52
	s_addc_u32 s53, s77, s53
	s_and_b64 s[78:79], s[18:19], exec
	s_cselect_b32 s41, s53, s63
	s_cselect_b32 s59, s52, s62
	s_add_u32 s20, s20, 0x100080
	s_addc_u32 s21, s21, 0
	s_add_u32 s81, s62, 0x100
	v_mov_b32_e32 v8, 0
	s_addc_u32 s82, s63, 0
	s_mov_b32 s83, -2
	v_mov_b32_e32 v9, v8
	v_mov_b32_e32 v10, v8
	v_mov_b32_e32 v11, v8
	v_mov_b32_e32 v4, v8
	v_mov_b32_e32 v5, v8
	v_mov_b32_e32 v6, v8
	v_mov_b32_e32 v7, v8
	v_mov_b32_e32 v12, v8
	v_mov_b32_e32 v13, v8
	v_mov_b32_e32 v14, v8
	v_mov_b32_e32 v15, v8
	v_mov_b32_e32 v16, v8
	v_mov_b32_e32 v17, v8
	v_mov_b32_e32 v18, v8
	v_mov_b32_e32 v19, v8
	v_mov_b32_e32 v20, v8
	v_mov_b32_e32 v21, v8
	v_mov_b32_e32 v22, v8
	v_mov_b32_e32 v23, v8
	v_mov_b32_e32 v24, v8
	v_mov_b32_e32 v25, v8
	v_mov_b32_e32 v26, v8
	v_mov_b32_e32 v27, v8
	v_mov_b32_e32 v28, v8
	v_mov_b32_e32 v29, v8
	v_mov_b32_e32 v30, v8
	v_mov_b32_e32 v31, v8
	v_mov_b32_e32 v32, v8
	v_mov_b32_e32 v33, v8
	v_mov_b32_e32 v34, v8
	v_mov_b32_e32 v35, v8
	v_mov_b32_e32 v78, v8
	v_mov_b32_e32 v79, v8
	v_mov_b32_e32 v80, v8
	v_mov_b32_e32 v81, v8
	v_mov_b32_e32 v74, v8
	v_mov_b32_e32 v75, v8
	v_mov_b32_e32 v76, v8
	v_mov_b32_e32 v77, v8
	v_mov_b32_e32 v68, v8
	v_mov_b32_e32 v69, v8
	v_mov_b32_e32 v70, v8
	v_mov_b32_e32 v71, v8
	v_mov_b32_e32 v82, v8
	v_mov_b32_e32 v83, v8
	v_mov_b32_e32 v84, v8
	v_mov_b32_e32 v85, v8
	v_mov_b32_e32 v86, v8
	v_mov_b32_e32 v87, v8
	v_mov_b32_e32 v88, v8
	v_mov_b32_e32 v89, v8
	v_mov_b32_e32 v90, v8
	v_mov_b32_e32 v91, v8
	v_mov_b32_e32 v92, v8
	v_mov_b32_e32 v93, v8
	v_mov_b32_e32 v94, v8
	v_mov_b32_e32 v95, v8
	v_mov_b32_e32 v96, v8
	v_mov_b32_e32 v97, v8
	v_mov_b32_e32 v98, v8
	v_mov_b32_e32 v99, v8
	v_mov_b32_e32 v100, v8
	v_mov_b32_e32 v101, v8
	v_mov_b32_e32 v36, v8
	v_mov_b32_e32 v37, v8
	v_mov_b32_e32 v38, v8
	v_mov_b32_e32 v39, v8
	v_mov_b32_e32 v40, v8
	v_mov_b32_e32 v41, v8
	v_mov_b32_e32 v42, v8
	v_mov_b32_e32 v43, v8
	v_mov_b32_e32 v44, v8
	v_mov_b32_e32 v45, v8
	v_mov_b32_e32 v46, v8
	v_mov_b32_e32 v47, v8
	v_mov_b32_e32 v48, v8
	v_mov_b32_e32 v49, v8
	v_mov_b32_e32 v50, v8
	v_mov_b32_e32 v51, v8
	v_mov_b32_e32 v52, v8
	v_mov_b32_e32 v53, v8
	v_mov_b32_e32 v54, v8
	v_mov_b32_e32 v55, v8
	v_mov_b32_e32 v56, v8
	v_mov_b32_e32 v57, v8
	v_mov_b32_e32 v58, v8
	v_mov_b32_e32 v59, v8
	v_mov_b32_e32 v60, v8
	v_mov_b32_e32 v61, v8
	v_mov_b32_e32 v62, v8
	v_mov_b32_e32 v63, v8
	v_mov_b32_e32 v64, v8
	v_mov_b32_e32 v65, v8
	v_mov_b32_e32 v66, v8
	v_mov_b32_e32 v67, v8
	v_mov_b32_e32 v102, v8
	v_mov_b32_e32 v103, v8
	v_mov_b32_e32 v104, v8
	v_mov_b32_e32 v105, v8
	v_mov_b32_e32 v106, v8
	v_mov_b32_e32 v107, v8
	v_mov_b32_e32 v108, v8
	v_mov_b32_e32 v109, v8
	v_mov_b32_e32 v110, v8
	v_mov_b32_e32 v111, v8
	v_mov_b32_e32 v112, v8
	v_mov_b32_e32 v113, v8
	v_mov_b32_e32 v114, v8
	v_mov_b32_e32 v115, v8
	v_mov_b32_e32 v116, v8
	v_mov_b32_e32 v117, v8
	v_mov_b32_e32 v118, v8
	v_mov_b32_e32 v119, v8
	v_mov_b32_e32 v120, v8
	v_mov_b32_e32 v121, v8
	v_mov_b32_e32 v122, v8
	v_mov_b32_e32 v123, v8
	v_mov_b32_e32 v124, v8
	v_mov_b32_e32 v125, v8
	v_mov_b32_e32 v126, v8
	v_mov_b32_e32 v127, v8
	v_mov_b32_e32 v128, v8
	v_mov_b32_e32 v129, v8
	v_mov_b32_e32 v130, v8
	v_mov_b32_e32 v131, v8
	v_mov_b32_e32 v132, v8
	v_mov_b32_e32 v133, v8
	s_cmp_lt_u32 s89, 4
	s_cbranch_scc1 .Lprio_528
	s_setprio 1
.Lprio_528:
.LBB0_528:
	ds_read_b128 v[134:137], v200
	ds_read_b128 v[138:141], v200 offset:1024
	ds_read_b128 v[162:165], v200 offset:2048
	ds_read_b128 v[166:169], v200 offset:3072
	ds_read_b128 v[170:173], v201
	ds_read_b128 v[174:177], v201 offset:1024
	ds_read_b128 v[178:181], v201 offset:2048
	ds_read_b128 v[206:209], v201 offset:3072
	s_add_u32 s62, s20, 0xfff00080
	s_addc_u32 s63, s21, -1
	s_cmp_eq_u32 s83, 60
	s_cselect_b32 s79, s47, s63
	s_cselect_b32 s78, s57, s62
	s_cselect_b32 s63, s41, s82
	s_cselect_b32 s62, s59, s81
	s_add_u32 s98, s62, s30
	s_addc_u32 s99, s63, s31
	s_add_u32 s100, s78, s30
	s_addc_u32 s101, s79, s31
	s_add_i32 m0, s39, 0xc000
	ds_read_b128 v[210:213], v202
	ds_read_b128 v[214:217], v202 offset:1024
	ds_read_b128 v[218:221], v202 offset:2048
	ds_read_b128 v[222:225], v202 offset:3072
	ds_read_b128 v[226:229], v202 offset:4096
	ds_read_b128 v[230:233], v202 offset:5120
	ds_read_b128 v[234:237], v202 offset:6144
	ds_read_b128 v[238:241], v202 offset:7168
	global_load_lds_dwordx4 v154, s[20:21]
	s_add_i32 m0, s39, 0xe000
	s_nop 0
	global_load_lds_dwordx4 v156, s[20:21]
	s_waitcnt vmcnt(8)
	s_waitcnt lgkmcnt(0)
	s_barrier
	s_waitcnt lgkmcnt(0)
	v_mfma_f32_16x16x32_bf16 v[130:133], v[210:213], v[134:137], v[130:133]
	v_mfma_f32_16x16x32_bf16 v[126:129], v[210:213], v[162:165], v[126:129]
	v_mfma_f32_16x16x32_bf16 v[122:125], v[218:221], v[134:137], v[122:125]
	v_mfma_f32_16x16x32_bf16 v[118:121], v[218:221], v[162:165], v[118:121]
	v_mfma_f32_16x16x32_bf16 v[114:117], v[226:229], v[134:137], v[114:117]
	v_mfma_f32_16x16x32_bf16 v[110:113], v[226:229], v[162:165], v[110:113]
	v_mfma_f32_16x16x32_bf16 v[106:109], v[234:237], v[134:137], v[106:109]
	v_mfma_f32_16x16x32_bf16 v[102:105], v[234:237], v[162:165], v[102:105]
	v_mfma_f32_16x16x32_bf16 v[130:133], v[214:217], v[138:141], v[130:133]
	v_mfma_f32_16x16x32_bf16 v[126:129], v[214:217], v[166:169], v[126:129]
	v_mfma_f32_16x16x32_bf16 v[122:125], v[222:225], v[138:141], v[122:125]
	v_mfma_f32_16x16x32_bf16 v[118:121], v[222:225], v[166:169], v[118:121]
	v_mfma_f32_16x16x32_bf16 v[114:117], v[230:233], v[138:141], v[114:117]
	v_mfma_f32_16x16x32_bf16 v[110:113], v[230:233], v[166:169], v[110:113]
	v_mfma_f32_16x16x32_bf16 v[106:109], v[238:241], v[138:141], v[106:109]
	v_mfma_f32_16x16x32_bf16 v[102:105], v[238:241], v[166:169], v[102:105]
	v_mfma_f32_16x16x32_bf16 v[64:67], v[170:173], v[210:213], v[64:67]
	v_mfma_f32_16x16x32_bf16 v[60:63], v[178:181], v[210:213], v[60:63]
	v_mfma_f32_16x16x32_bf16 v[56:59], v[170:173], v[218:221], v[56:59]
	v_mfma_f32_16x16x32_bf16 v[52:55], v[178:181], v[218:221], v[52:55]
	v_mfma_f32_16x16x32_bf16 v[48:51], v[170:173], v[226:229], v[48:51]
	v_mfma_f32_16x16x32_bf16 v[44:47], v[178:181], v[226:229], v[44:47]
	v_mfma_f32_16x16x32_bf16 v[40:43], v[170:173], v[234:237], v[40:43]
	v_mfma_f32_16x16x32_bf16 v[36:39], v[178:181], v[234:237], v[36:39]
	v_mfma_f32_16x16x32_bf16 v[64:67], v[174:177], v[214:217], v[64:67]
	v_mfma_f32_16x16x32_bf16 v[60:63], v[206:209], v[214:217], v[60:63]
	v_mfma_f32_16x16x32_bf16 v[56:59], v[174:177], v[222:225], v[56:59]
	v_mfma_f32_16x16x32_bf16 v[52:55], v[206:209], v[222:225], v[52:55]
	v_mfma_f32_16x16x32_bf16 v[48:51], v[174:177], v[230:233], v[48:51]
	v_mfma_f32_16x16x32_bf16 v[44:47], v[206:209], v[230:233], v[44:47]
	v_mfma_f32_16x16x32_bf16 v[40:43], v[174:177], v[238:241], v[40:43]
	v_mfma_f32_16x16x32_bf16 v[36:39], v[206:209], v[238:241], v[36:39]
	s_barrier
	s_add_i32 s84, s75, s3
	s_mov_b32 m0, s84
	ds_read_b128 v[210:213], v202 offset:16384
	ds_read_b128 v[214:217], v202 offset:17408
	ds_read_b128 v[218:221], v202 offset:18432
	ds_read_b128 v[222:225], v202 offset:19456
	ds_read_b128 v[226:229], v202 offset:20480
	ds_read_b128 v[230:233], v202 offset:21504
	ds_read_b128 v[234:237], v202 offset:22528
	ds_read_b128 v[238:241], v202 offset:23552
	global_load_lds_dwordx4 v144, s[62:63]
	s_add_i32 m0, s84, 0x2000
	s_add_u32 s84, s62, 0x100000
	s_addc_u32 s85, s63, 0
	s_add_i32 s86, s80, s3
	global_load_lds_dwordx4 v148, s[62:63]
	s_mov_b32 m0, s86
	s_nop 0
	global_load_lds_dwordx4 v144, s[84:85]
	s_add_i32 m0, s86, 0x2000
	s_nop 0
	global_load_lds_dwordx4 v148, s[84:85]
	s_mov_b32 m0, s39
	s_nop 0
	global_load_lds_dwordx4 v142, s[78:79]
	s_mov_b32 m0, s54
	s_nop 0
	global_load_lds_dwordx4 v146, s[78:79]
	s_waitcnt vmcnt(8)
	s_waitcnt lgkmcnt(0)
	s_barrier
	s_waitcnt lgkmcnt(0)
	v_mfma_f32_16x16x32_bf16 v[98:101], v[210:213], v[134:137], v[98:101]
	v_mfma_f32_16x16x32_bf16 v[94:97], v[210:213], v[162:165], v[94:97]
	v_mfma_f32_16x16x32_bf16 v[90:93], v[218:221], v[134:137], v[90:93]
	v_mfma_f32_16x16x32_bf16 v[86:89], v[218:221], v[162:165], v[86:89]
	v_mfma_f32_16x16x32_bf16 v[82:85], v[226:229], v[134:137], v[82:85]
	v_mfma_f32_16x16x32_bf16 v[68:71], v[226:229], v[162:165], v[68:71]
	v_mfma_f32_16x16x32_bf16 v[72:75], v[234:237], v[134:137], v[74:77]
	v_mfma_f32_16x16x32_bf16 v[76:79], v[234:237], v[162:165], v[78:81]
	v_mfma_f32_16x16x32_bf16 v[98:101], v[214:217], v[138:141], v[98:101]
	v_mfma_f32_16x16x32_bf16 v[94:97], v[214:217], v[166:169], v[94:97]
	v_mfma_f32_16x16x32_bf16 v[90:93], v[222:225], v[138:141], v[90:93]
	v_mfma_f32_16x16x32_bf16 v[86:89], v[222:225], v[166:169], v[86:89]
	v_mfma_f32_16x16x32_bf16 v[82:85], v[230:233], v[138:141], v[82:85]
	v_mfma_f32_16x16x32_bf16 v[68:71], v[230:233], v[166:169], v[68:71]
	v_mfma_f32_16x16x32_bf16 v[72:75], v[238:241], v[138:141], v[72:75]
	v_mfma_f32_16x16x32_bf16 v[78:81], v[238:241], v[166:169], v[76:79]
	v_mfma_f32_16x16x32_bf16 v[32:35], v[170:173], v[210:213], v[32:35]
	v_mfma_f32_16x16x32_bf16 v[28:31], v[178:181], v[210:213], v[28:31]
	v_mfma_f32_16x16x32_bf16 v[24:27], v[170:173], v[218:221], v[24:27]
	v_mfma_f32_16x16x32_bf16 v[20:23], v[178:181], v[218:221], v[20:23]
	v_mfma_f32_16x16x32_bf16 v[16:19], v[170:173], v[226:229], v[16:19]
	v_mfma_f32_16x16x32_bf16 v[12:15], v[178:181], v[226:229], v[12:15]
	v_mfma_f32_16x16x32_bf16 v[2:5], v[170:173], v[234:237], v[4:7]
	v_mfma_f32_16x16x32_bf16 v[6:9], v[178:181], v[234:237], v[8:11]
	v_mfma_f32_16x16x32_bf16 v[32:35], v[174:177], v[214:217], v[32:35]
	v_mfma_f32_16x16x32_bf16 v[28:31], v[206:209], v[214:217], v[28:31]
	v_mfma_f32_16x16x32_bf16 v[24:27], v[174:177], v[222:225], v[24:27]
	v_mfma_f32_16x16x32_bf16 v[20:23], v[206:209], v[222:225], v[20:23]
	v_mfma_f32_16x16x32_bf16 v[16:19], v[174:177], v[230:233], v[16:19]
	v_mfma_f32_16x16x32_bf16 v[12:15], v[206:209], v[230:233], v[12:15]
	v_mfma_f32_16x16x32_bf16 v[2:5], v[174:177], v[238:241], v[2:5]
	v_mfma_f32_16x16x32_bf16 v[8:11], v[206:209], v[238:241], v[6:9]
	s_barrier
	s_add_i32 s84, 0, 0x18000
	v_add_u32_e32 v1, s84, v183
	s_add_i32 s85, 0, 0x1c000
	ds_read_b128 v[134:137], v1
	ds_read_b128 v[138:141], v1 offset:1024
	ds_read_b128 v[162:165], v1 offset:2048
	ds_read_b128 v[166:169], v1 offset:3072
	v_add_u32_e32 v1, s85, v183
	ds_read_b128 v[170:173], v1
	ds_read_b128 v[174:177], v1 offset:1024
	ds_read_b128 v[178:181], v1 offset:2048
	ds_read_b128 v[206:209], v1 offset:3072
	s_add_u32 s78, s78, 0x100000
	s_addc_u32 s79, s79, 0
	s_mov_b32 m0, s55
	ds_read_b128 v[210:213], v202 offset:32768
	ds_read_b128 v[214:217], v202 offset:33792
	ds_read_b128 v[218:221], v202 offset:34816
	ds_read_b128 v[222:225], v202 offset:35840
	ds_read_b128 v[226:229], v202 offset:36864
	ds_read_b128 v[230:233], v202 offset:37888
	ds_read_b128 v[234:237], v202 offset:38912
	ds_read_b128 v[238:241], v202 offset:39936
	global_load_lds_dwordx4 v142, s[78:79]
	s_mov_b32 m0, s68
	s_nop 0
	global_load_lds_dwordx4 v146, s[78:79]
	s_waitcnt vmcnt(8)
	s_waitcnt lgkmcnt(0)
	s_barrier
	s_waitcnt lgkmcnt(0)
	v_mfma_f32_16x16x32_bf16 v[130:133], v[210:213], v[134:137], v[130:133]
	v_mfma_f32_16x16x32_bf16 v[126:129], v[210:213], v[162:165], v[126:129]
	v_mfma_f32_16x16x32_bf16 v[122:125], v[218:221], v[134:137], v[122:125]
	v_mfma_f32_16x16x32_bf16 v[118:121], v[218:221], v[162:165], v[118:121]
	v_mfma_f32_16x16x32_bf16 v[114:117], v[226:229], v[134:137], v[114:117]
	v_mfma_f32_16x16x32_bf16 v[110:113], v[226:229], v[162:165], v[110:113]
	v_mfma_f32_16x16x32_bf16 v[106:109], v[234:237], v[134:137], v[106:109]
	v_mfma_f32_16x16x32_bf16 v[102:105], v[234:237], v[162:165], v[102:105]
	v_mfma_f32_16x16x32_bf16 v[130:133], v[214:217], v[138:141], v[130:133]
	v_mfma_f32_16x16x32_bf16 v[126:129], v[214:217], v[166:169], v[126:129]
	v_mfma_f32_16x16x32_bf16 v[122:125], v[222:225], v[138:141], v[122:125]
	v_mfma_f32_16x16x32_bf16 v[118:121], v[222:225], v[166:169], v[118:121]
	v_mfma_f32_16x16x32_bf16 v[114:117], v[230:233], v[138:141], v[114:117]
	v_mfma_f32_16x16x32_bf16 v[110:113], v[230:233], v[166:169], v[110:113]
	v_mfma_f32_16x16x32_bf16 v[106:109], v[238:241], v[138:141], v[106:109]
	v_mfma_f32_16x16x32_bf16 v[102:105], v[238:241], v[166:169], v[102:105]
	v_mfma_f32_16x16x32_bf16 v[64:67], v[170:173], v[210:213], v[64:67]
	v_mfma_f32_16x16x32_bf16 v[60:63], v[178:181], v[210:213], v[60:63]
	v_mfma_f32_16x16x32_bf16 v[56:59], v[170:173], v[218:221], v[56:59]
	v_mfma_f32_16x16x32_bf16 v[52:55], v[178:181], v[218:221], v[52:55]
	v_mfma_f32_16x16x32_bf16 v[48:51], v[170:173], v[226:229], v[48:51]
	v_mfma_f32_16x16x32_bf16 v[44:47], v[178:181], v[226:229], v[44:47]
	v_mfma_f32_16x16x32_bf16 v[40:43], v[170:173], v[234:237], v[40:43]
	v_mfma_f32_16x16x32_bf16 v[36:39], v[178:181], v[234:237], v[36:39]
	v_mfma_f32_16x16x32_bf16 v[64:67], v[174:177], v[214:217], v[64:67]
	v_mfma_f32_16x16x32_bf16 v[60:63], v[206:209], v[214:217], v[60:63]
	v_mfma_f32_16x16x32_bf16 v[56:59], v[174:177], v[222:225], v[56:59]
	v_mfma_f32_16x16x32_bf16 v[52:55], v[206:209], v[222:225], v[52:55]
	v_mfma_f32_16x16x32_bf16 v[48:51], v[174:177], v[230:233], v[48:51]
	v_mfma_f32_16x16x32_bf16 v[44:47], v[206:209], v[230:233], v[44:47]
	v_mfma_f32_16x16x32_bf16 v[40:43], v[174:177], v[238:241], v[40:43]
	v_mfma_f32_16x16x32_bf16 v[36:39], v[206:209], v[238:241], v[36:39]
	s_barrier
	s_add_i32 s78, s84, s3
	s_mov_b32 m0, s78
	ds_read_b128 v[210:213], v202 offset:49152
	ds_read_b128 v[214:217], v202 offset:50176
	ds_read_b128 v[218:221], v202 offset:51200
	ds_read_b128 v[222:225], v202 offset:52224
	ds_read_b128 v[226:229], v202 offset:53248
	ds_read_b128 v[230:233], v202 offset:54272
	ds_read_b128 v[234:237], v202 offset:55296
	ds_read_b128 v[238:241], v202 offset:56320
	global_load_lds_dwordx4 v144, s[98:99]
	s_add_i32 m0, s78, 0x2000
	s_add_u32 s62, s62, 0x100080
	s_addc_u32 s63, s63, 0
	s_add_i32 s78, s85, s3
	global_load_lds_dwordx4 v148, s[98:99]
	s_mov_b32 m0, s78
	s_nop 0
	global_load_lds_dwordx4 v144, s[62:63]
	s_add_i32 m0, s78, 0x2000
	s_nop 0
	global_load_lds_dwordx4 v148, s[62:63]
	s_mov_b32 m0, s71
	s_nop 0
	global_load_lds_dwordx4 v142, s[100:101]
	s_mov_b32 m0, s72
	s_nop 0
	global_load_lds_dwordx4 v146, s[100:101]
	s_waitcnt vmcnt(8)
	s_waitcnt lgkmcnt(0)
	s_barrier
	s_waitcnt lgkmcnt(0)
	v_mfma_f32_16x16x32_bf16 v[98:101], v[210:213], v[134:137], v[98:101]
	v_mfma_f32_16x16x32_bf16 v[94:97], v[210:213], v[162:165], v[94:97]
	v_mfma_f32_16x16x32_bf16 v[90:93], v[218:221], v[134:137], v[90:93]
	v_mfma_f32_16x16x32_bf16 v[86:89], v[218:221], v[162:165], v[86:89]
	v_mfma_f32_16x16x32_bf16 v[82:85], v[226:229], v[134:137], v[82:85]
	v_mfma_f32_16x16x32_bf16 v[68:71], v[226:229], v[162:165], v[68:71]
	v_mfma_f32_16x16x32_bf16 v[72:75], v[234:237], v[134:137], v[72:75]
	v_mfma_f32_16x16x32_bf16 v[78:81], v[234:237], v[162:165], v[78:81]
	v_mfma_f32_16x16x32_bf16 v[98:101], v[214:217], v[138:141], v[98:101]
	v_mfma_f32_16x16x32_bf16 v[94:97], v[214:217], v[166:169], v[94:97]
	v_mfma_f32_16x16x32_bf16 v[90:93], v[222:225], v[138:141], v[90:93]
	v_mfma_f32_16x16x32_bf16 v[86:89], v[222:225], v[166:169], v[86:89]
	v_mfma_f32_16x16x32_bf16 v[82:85], v[230:233], v[138:141], v[82:85]
	v_mfma_f32_16x16x32_bf16 v[68:71], v[230:233], v[166:169], v[68:71]
	v_mfma_f32_16x16x32_bf16 v[74:77], v[238:241], v[138:141], v[72:75]
	v_mfma_f32_16x16x32_bf16 v[78:81], v[238:241], v[166:169], v[78:81]
	v_mfma_f32_16x16x32_bf16 v[32:35], v[170:173], v[210:213], v[32:35]
	v_mfma_f32_16x16x32_bf16 v[28:31], v[178:181], v[210:213], v[28:31]
	v_mfma_f32_16x16x32_bf16 v[24:27], v[170:173], v[218:221], v[24:27]
	v_mfma_f32_16x16x32_bf16 v[20:23], v[178:181], v[218:221], v[20:23]
	v_mfma_f32_16x16x32_bf16 v[16:19], v[170:173], v[226:229], v[16:19]
	v_mfma_f32_16x16x32_bf16 v[12:15], v[178:181], v[226:229], v[12:15]
	v_mfma_f32_16x16x32_bf16 v[2:5], v[170:173], v[234:237], v[2:5]
	v_mfma_f32_16x16x32_bf16 v[8:11], v[178:181], v[234:237], v[8:11]
	v_mfma_f32_16x16x32_bf16 v[32:35], v[174:177], v[214:217], v[32:35]
	v_mfma_f32_16x16x32_bf16 v[28:31], v[206:209], v[214:217], v[28:31]
	v_mfma_f32_16x16x32_bf16 v[24:27], v[174:177], v[222:225], v[24:27]
	v_mfma_f32_16x16x32_bf16 v[20:23], v[206:209], v[222:225], v[20:23]
	v_mfma_f32_16x16x32_bf16 v[16:19], v[174:177], v[230:233], v[16:19]
	v_mfma_f32_16x16x32_bf16 v[12:15], v[206:209], v[230:233], v[12:15]
	v_mfma_f32_16x16x32_bf16 v[4:7], v[174:177], v[238:241], v[2:5]
	v_mfma_f32_16x16x32_bf16 v[8:11], v[206:209], v[238:241], v[8:11]
	s_barrier
	s_add_i32 s83, s83, 2
	s_add_u32 s20, s20, 0x100
	s_addc_u32 s21, s21, 0
	s_add_u32 s81, s81, 0x100
	s_addc_u32 s82, s82, 0
	s_cmp_gt_u32 s83, 61
	s_cbranch_scc0 .LBB0_528
	s_setprio 0
	s_and_b64 vcc, exec, s[34:35]
	s_cbranch_vccz .LBB0_531
	s_barrier

.LBB0_814:
	s_ashr_i32 s29, s28, 31
	s_lshl_b64 s[34:35], s[28:29], 22
	s_add_u32 s34, s48, s34
	s_addc_u32 s35, s49, s35
	s_and_b64 s[36:37], s[4:5], exec
	s_cselect_b32 s29, s35, s47
	s_cselect_b32 s39, s34, s46
	s_ashr_i32 s31, s30, 31
	s_lshl_b64 s[36:37], s[30:31], 22
	v_readlane_b32 s52, v254, 7
	v_readlane_b32 s53, v254, 8
	s_add_u32 s36, s52, s36
	s_addc_u32 s37, s53, s37
	s_and_b64 s[52:53], s[4:5], exec
	s_cselect_b32 s31, s37, s51
	s_cselect_b32 s41, s36, s50
	s_add_u32 s46, s46, 0x200080
	s_addc_u32 s47, s47, 0
	s_add_u32 s75, s50, 0x100
	v_mov_b32_e32 v0, 0
	s_addc_u32 s76, s51, 0
	s_mov_b32 s77, -2
	v_mov_b32_e32 v1, v0
	v_mov_b32_e32 v2, v0
	v_mov_b32_e32 v3, v0
	v_mov_b32_e32 v4, v0
	v_mov_b32_e32 v5, v0
	v_mov_b32_e32 v6, v0
	v_mov_b32_e32 v7, v0
	v_mov_b32_e32 v16, v0
	v_mov_b32_e32 v17, v0
	v_mov_b32_e32 v18, v0
	v_mov_b32_e32 v19, v0
	v_mov_b32_e32 v20, v0
	v_mov_b32_e32 v21, v0
	v_mov_b32_e32 v22, v0
	v_mov_b32_e32 v23, v0
	v_mov_b32_e32 v32, v0
	v_mov_b32_e32 v33, v0
	v_mov_b32_e32 v34, v0
	v_mov_b32_e32 v35, v0
	v_mov_b32_e32 v36, v0
	v_mov_b32_e32 v37, v0
	v_mov_b32_e32 v38, v0
	v_mov_b32_e32 v39, v0
	v_mov_b32_e32 v48, v0
	v_mov_b32_e32 v49, v0
	v_mov_b32_e32 v50, v0
	v_mov_b32_e32 v51, v0
	v_mov_b32_e32 v52, v0
	v_mov_b32_e32 v53, v0
	v_mov_b32_e32 v54, v0
	v_mov_b32_e32 v55, v0
	v_mov_b32_e32 v8, v0
	v_mov_b32_e32 v9, v0
	v_mov_b32_e32 v10, v0
	v_mov_b32_e32 v11, v0
	v_mov_b32_e32 v12, v0
	v_mov_b32_e32 v13, v0
	v_mov_b32_e32 v14, v0
	v_mov_b32_e32 v15, v0
	v_mov_b32_e32 v24, v0
	v_mov_b32_e32 v25, v0
	v_mov_b32_e32 v26, v0
	v_mov_b32_e32 v27, v0
	v_mov_b32_e32 v28, v0
	v_mov_b32_e32 v29, v0
	v_mov_b32_e32 v30, v0
	v_mov_b32_e32 v31, v0
	v_mov_b32_e32 v40, v0
	v_mov_b32_e32 v41, v0
	v_mov_b32_e32 v42, v0
	v_mov_b32_e32 v43, v0
	v_mov_b32_e32 v44, v0
	v_mov_b32_e32 v45, v0
	v_mov_b32_e32 v46, v0
	v_mov_b32_e32 v47, v0
	v_mov_b32_e32 v72, v0
	v_mov_b32_e32 v73, v0
	v_mov_b32_e32 v74, v0
	v_mov_b32_e32 v75, v0
	v_mov_b32_e32 v76, v0
	v_mov_b32_e32 v77, v0
	v_mov_b32_e32 v78, v0
	v_mov_b32_e32 v79, v0
	v_mov_b32_e32 v80, v0
	v_mov_b32_e32 v81, v0
	v_mov_b32_e32 v82, v0
	v_mov_b32_e32 v83, v0
	v_mov_b32_e32 v84, v0
	v_mov_b32_e32 v85, v0
	v_mov_b32_e32 v86, v0
	v_mov_b32_e32 v87, v0
	v_mov_b32_e32 v96, v0
	v_mov_b32_e32 v97, v0
	v_mov_b32_e32 v98, v0
	v_mov_b32_e32 v99, v0
	v_mov_b32_e32 v100, v0
	v_mov_b32_e32 v101, v0
	v_mov_b32_e32 v102, v0
	v_mov_b32_e32 v103, v0
	v_mov_b32_e32 v112, v0
	v_mov_b32_e32 v113, v0
	v_mov_b32_e32 v114, v0
	v_mov_b32_e32 v115, v0
	v_mov_b32_e32 v116, v0
	v_mov_b32_e32 v117, v0
	v_mov_b32_e32 v118, v0
	v_mov_b32_e32 v119, v0
	v_mov_b32_e32 v128, v0
	v_mov_b32_e32 v129, v0
	v_mov_b32_e32 v130, v0
	v_mov_b32_e32 v131, v0
	v_mov_b32_e32 v132, v0
	v_mov_b32_e32 v133, v0
	v_mov_b32_e32 v134, v0
	v_mov_b32_e32 v135, v0
	v_mov_b32_e32 v88, v0
	v_mov_b32_e32 v89, v0
	v_mov_b32_e32 v90, v0
	v_mov_b32_e32 v91, v0
	v_mov_b32_e32 v92, v0
	v_mov_b32_e32 v93, v0
	v_mov_b32_e32 v94, v0
	v_mov_b32_e32 v95, v0
	v_mov_b32_e32 v104, v0
	v_mov_b32_e32 v105, v0
	v_mov_b32_e32 v106, v0
	v_mov_b32_e32 v107, v0
	v_mov_b32_e32 v108, v0
	v_mov_b32_e32 v109, v0
	v_mov_b32_e32 v110, v0
	v_mov_b32_e32 v111, v0
	v_mov_b32_e32 v120, v0
	v_mov_b32_e32 v121, v0
	v_mov_b32_e32 v122, v0
	v_mov_b32_e32 v123, v0
	v_mov_b32_e32 v124, v0
	v_mov_b32_e32 v125, v0
	v_mov_b32_e32 v126, v0
	v_mov_b32_e32 v127, v0
	v_mov_b32_e32 v136, v0
	v_mov_b32_e32 v137, v0
	v_mov_b32_e32 v138, v0
	v_mov_b32_e32 v139, v0
	v_mov_b32_e32 v140, v0
	v_mov_b32_e32 v141, v0
	v_mov_b32_e32 v142, v0
	v_mov_b32_e32 v143, v0
	s_cmp_lt_u32 s89, 4
	s_cbranch_scc1 .Lprio_815
	s_setprio 1
.Lprio_815:
.LBB0_815:
	ds_read_b128 v[56:59], v241
	ds_read_b128 v[60:63], v241 offset:1024
	ds_read_b128 v[64:67], v241 offset:2048
	ds_read_b128 v[68:71], v241 offset:3072
	ds_read_b128 v[144:147], v242
	ds_read_b128 v[148:151], v242 offset:1024
	ds_read_b128 v[152:155], v242 offset:2048
	ds_read_b128 v[156:159], v242 offset:3072
	s_add_u32 s50, s46, 0xffe00080
	s_addc_u32 s51, s47, -1
	s_cmpk_eq_i32 s77, 0x7c
	s_cselect_b32 s53, s29, s51
	s_cselect_b32 s52, s39, s50
	s_cselect_b32 s51, s31, s76
	s_cselect_b32 s50, s41, s75
	s_add_u32 s98, s50, s12
	s_addc_u32 s99, s51, s13
	s_add_u32 s100, s52, s12
	s_addc_u32 s101, s53, s13
	s_add_i32 m0, s55, 0xc000
	ds_read_b128 v[160:163], v243
	ds_read_b128 v[164:167], v243 offset:1024
	ds_read_b128 v[168:171], v243 offset:2048
	ds_read_b128 v[172:175], v243 offset:3072
	ds_read_b128 v[176:179], v243 offset:4096
	ds_read_b128 v[180:183], v243 offset:5120
	ds_read_b128 v[184:187], v243 offset:6144
	ds_read_b128 v[188:191], v243 offset:7168
	global_load_lds_dwordx4 v216, s[46:47]
	s_add_i32 m0, s55, 0xe000
	s_nop 0
	global_load_lds_dwordx4 v218, s[46:47]
	s_waitcnt vmcnt(8)
	s_waitcnt lgkmcnt(0)
	s_barrier
	s_waitcnt lgkmcnt(0)
	v_mfma_f32_16x16x32_bf16 v[140:143], v[56:59], v[160:163], v[140:143]
	v_mfma_f32_16x16x32_bf16 v[136:139], v[64:67], v[160:163], v[136:139]
	v_mfma_f32_16x16x32_bf16 v[124:127], v[56:59], v[168:171], v[124:127]
	v_mfma_f32_16x16x32_bf16 v[120:123], v[64:67], v[168:171], v[120:123]
	v_mfma_f32_16x16x32_bf16 v[108:111], v[56:59], v[176:179], v[108:111]
	v_mfma_f32_16x16x32_bf16 v[104:107], v[64:67], v[176:179], v[104:107]
	v_mfma_f32_16x16x32_bf16 v[92:95], v[56:59], v[184:187], v[92:95]
	v_mfma_f32_16x16x32_bf16 v[88:91], v[64:67], v[184:187], v[88:91]
	v_mfma_f32_16x16x32_bf16 v[140:143], v[60:63], v[164:167], v[140:143]
	v_mfma_f32_16x16x32_bf16 v[136:139], v[68:71], v[164:167], v[136:139]
	v_mfma_f32_16x16x32_bf16 v[124:127], v[60:63], v[172:175], v[124:127]
	v_mfma_f32_16x16x32_bf16 v[120:123], v[68:71], v[172:175], v[120:123]
	v_mfma_f32_16x16x32_bf16 v[108:111], v[60:63], v[180:183], v[108:111]
	v_mfma_f32_16x16x32_bf16 v[104:107], v[68:71], v[180:183], v[104:107]
	v_mfma_f32_16x16x32_bf16 v[92:95], v[60:63], v[188:191], v[92:95]
	v_mfma_f32_16x16x32_bf16 v[88:91], v[68:71], v[188:191], v[88:91]
	v_mfma_f32_16x16x32_bf16 v[132:135], v[144:147], v[160:163], v[132:135]
	v_mfma_f32_16x16x32_bf16 v[128:131], v[152:155], v[160:163], v[128:131]
	v_mfma_f32_16x16x32_bf16 v[116:119], v[144:147], v[168:171], v[116:119]
	v_mfma_f32_16x16x32_bf16 v[112:115], v[152:155], v[168:171], v[112:115]
	v_mfma_f32_16x16x32_bf16 v[100:103], v[144:147], v[176:179], v[100:103]
	v_mfma_f32_16x16x32_bf16 v[96:99], v[152:155], v[176:179], v[96:99]
	v_mfma_f32_16x16x32_bf16 v[84:87], v[144:147], v[184:187], v[84:87]
	v_mfma_f32_16x16x32_bf16 v[80:83], v[152:155], v[184:187], v[80:83]
	v_mfma_f32_16x16x32_bf16 v[132:135], v[148:151], v[164:167], v[132:135]
	v_mfma_f32_16x16x32_bf16 v[128:131], v[156:159], v[164:167], v[128:131]
	v_mfma_f32_16x16x32_bf16 v[116:119], v[148:151], v[172:175], v[116:119]
	v_mfma_f32_16x16x32_bf16 v[112:115], v[156:159], v[172:175], v[112:115]
	v_mfma_f32_16x16x32_bf16 v[100:103], v[148:151], v[180:183], v[100:103]
	v_mfma_f32_16x16x32_bf16 v[96:99], v[156:159], v[180:183], v[96:99]
	v_mfma_f32_16x16x32_bf16 v[84:87], v[148:151], v[188:191], v[84:87]
	v_mfma_f32_16x16x32_bf16 v[80:83], v[156:159], v[188:191], v[80:83]
	s_barrier
	s_add_i32 s78, s73, s54
	s_mov_b32 m0, s78
	ds_read_b128 v[160:163], v243 offset:16384
	ds_read_b128 v[164:167], v243 offset:17408
	ds_read_b128 v[168:171], v243 offset:18432
	ds_read_b128 v[172:175], v243 offset:19456
	ds_read_b128 v[176:179], v243 offset:20480
	ds_read_b128 v[180:183], v243 offset:21504
	ds_read_b128 v[184:187], v243 offset:22528
	ds_read_b128 v[188:191], v243 offset:23552
	global_load_lds_dwordx4 v210, s[50:51]
	s_add_i32 m0, s78, 0x2000
	s_add_u32 s78, s50, 0x200000
	s_addc_u32 s79, s51, 0
	s_add_i32 s80, s74, s54
	global_load_lds_dwordx4 v214, s[50:51]
	s_mov_b32 m0, s80
	s_nop 0
	global_load_lds_dwordx4 v210, s[78:79]
	s_add_i32 m0, s80, 0x2000
	s_nop 0
	global_load_lds_dwordx4 v214, s[78:79]
	s_mov_b32 m0, s55
	s_nop 0
	global_load_lds_dwordx4 v208, s[52:53]
	s_mov_b32 m0, s56
	s_nop 0
	global_load_lds_dwordx4 v212, s[52:53]
	s_waitcnt vmcnt(8)
	s_waitcnt lgkmcnt(0)
	s_barrier
	s_waitcnt lgkmcnt(0)
	v_mfma_f32_16x16x32_bf16 v[76:79], v[56:59], v[160:163], v[76:79]
	v_mfma_f32_16x16x32_bf16 v[72:75], v[64:67], v[160:163], v[72:75]
	v_mfma_f32_16x16x32_bf16 v[44:47], v[56:59], v[168:171], v[44:47]
	v_mfma_f32_16x16x32_bf16 v[40:43], v[64:67], v[168:171], v[40:43]
	v_mfma_f32_16x16x32_bf16 v[28:31], v[56:59], v[176:179], v[28:31]
	v_mfma_f32_16x16x32_bf16 v[24:27], v[64:67], v[176:179], v[24:27]
	v_mfma_f32_16x16x32_bf16 v[12:15], v[56:59], v[184:187], v[12:15]
	v_mfma_f32_16x16x32_bf16 v[8:11], v[64:67], v[184:187], v[8:11]
	v_mfma_f32_16x16x32_bf16 v[76:79], v[60:63], v[164:167], v[76:79]
	v_mfma_f32_16x16x32_bf16 v[72:75], v[68:71], v[164:167], v[72:75]
	v_mfma_f32_16x16x32_bf16 v[44:47], v[60:63], v[172:175], v[44:47]
	v_mfma_f32_16x16x32_bf16 v[40:43], v[68:71], v[172:175], v[40:43]
	v_mfma_f32_16x16x32_bf16 v[28:31], v[60:63], v[180:183], v[28:31]
	v_mfma_f32_16x16x32_bf16 v[24:27], v[68:71], v[180:183], v[24:27]
	v_mfma_f32_16x16x32_bf16 v[12:15], v[60:63], v[188:191], v[12:15]
	v_mfma_f32_16x16x32_bf16 v[8:11], v[68:71], v[188:191], v[8:11]
	v_mfma_f32_16x16x32_bf16 v[52:55], v[144:147], v[160:163], v[52:55]
	v_mfma_f32_16x16x32_bf16 v[48:51], v[152:155], v[160:163], v[48:51]
	v_mfma_f32_16x16x32_bf16 v[36:39], v[144:147], v[168:171], v[36:39]
	v_mfma_f32_16x16x32_bf16 v[32:35], v[152:155], v[168:171], v[32:35]
	v_mfma_f32_16x16x32_bf16 v[20:23], v[144:147], v[176:179], v[20:23]
	v_mfma_f32_16x16x32_bf16 v[16:19], v[152:155], v[176:179], v[16:19]
	v_mfma_f32_16x16x32_bf16 v[4:7], v[144:147], v[184:187], v[4:7]
	v_mfma_f32_16x16x32_bf16 v[0:3], v[152:155], v[184:187], v[0:3]
	v_mfma_f32_16x16x32_bf16 v[52:55], v[148:151], v[164:167], v[52:55]
	v_mfma_f32_16x16x32_bf16 v[48:51], v[156:159], v[164:167], v[48:51]
	v_mfma_f32_16x16x32_bf16 v[36:39], v[148:151], v[172:175], v[36:39]
	v_mfma_f32_16x16x32_bf16 v[32:35], v[156:159], v[172:175], v[32:35]
	v_mfma_f32_16x16x32_bf16 v[20:23], v[148:151], v[180:183], v[20:23]
	v_mfma_f32_16x16x32_bf16 v[16:19], v[156:159], v[180:183], v[16:19]
	v_mfma_f32_16x16x32_bf16 v[4:7], v[148:151], v[188:191], v[4:7]
	v_mfma_f32_16x16x32_bf16 v[0:3], v[156:159], v[188:191], v[0:3]
	s_barrier
	s_add_i32 s78, 0, 0x18000
	s_add_i32 s79, 0, 0x1c000
	v_add_u32_e32 v68, s78, v239
	v_add_u32_e32 v156, s79, v239
	ds_read_b128 v[56:59], v68
	ds_read_b128 v[60:63], v68 offset:1024
	ds_read_b128 v[64:67], v68 offset:2048
	ds_read_b128 v[68:71], v68 offset:3072
	ds_read_b128 v[144:147], v156
	ds_read_b128 v[148:151], v156 offset:1024
	ds_read_b128 v[152:155], v156 offset:2048
	ds_read_b128 v[156:159], v156 offset:3072
	s_add_u32 s52, s52, 0x200000
	s_addc_u32 s53, s53, 0
	s_mov_b32 m0, s57
	ds_read_b128 v[160:163], v243 offset:32768
	ds_read_b128 v[164:167], v243 offset:33792
	ds_read_b128 v[168:171], v243 offset:34816
	ds_read_b128 v[172:175], v243 offset:35840
	ds_read_b128 v[176:179], v243 offset:36864
	ds_read_b128 v[180:183], v243 offset:37888
	ds_read_b128 v[184:187], v243 offset:38912
	ds_read_b128 v[188:191], v243 offset:39936
	global_load_lds_dwordx4 v208, s[52:53]
	s_mov_b32 m0, s58
	s_nop 0
	global_load_lds_dwordx4 v212, s[52:53]
	s_waitcnt vmcnt(8)
	s_waitcnt lgkmcnt(0)
	s_barrier
	s_waitcnt lgkmcnt(0)
	v_mfma_f32_16x16x32_bf16 v[140:143], v[56:59], v[160:163], v[140:143]
	v_mfma_f32_16x16x32_bf16 v[136:139], v[64:67], v[160:163], v[136:139]
	v_mfma_f32_16x16x32_bf16 v[124:127], v[56:59], v[168:171], v[124:127]
	v_mfma_f32_16x16x32_bf16 v[120:123], v[64:67], v[168:171], v[120:123]
	v_mfma_f32_16x16x32_bf16 v[108:111], v[56:59], v[176:179], v[108:111]
	v_mfma_f32_16x16x32_bf16 v[104:107], v[64:67], v[176:179], v[104:107]
	v_mfma_f32_16x16x32_bf16 v[92:95], v[56:59], v[184:187], v[92:95]
	v_mfma_f32_16x16x32_bf16 v[88:91], v[64:67], v[184:187], v[88:91]
	v_mfma_f32_16x16x32_bf16 v[140:143], v[60:63], v[164:167], v[140:143]
	v_mfma_f32_16x16x32_bf16 v[136:139], v[68:71], v[164:167], v[136:139]
	v_mfma_f32_16x16x32_bf16 v[124:127], v[60:63], v[172:175], v[124:127]
	v_mfma_f32_16x16x32_bf16 v[120:123], v[68:71], v[172:175], v[120:123]
	v_mfma_f32_16x16x32_bf16 v[108:111], v[60:63], v[180:183], v[108:111]
	v_mfma_f32_16x16x32_bf16 v[104:107], v[68:71], v[180:183], v[104:107]
	v_mfma_f32_16x16x32_bf16 v[92:95], v[60:63], v[188:191], v[92:95]
	v_mfma_f32_16x16x32_bf16 v[88:91], v[68:71], v[188:191], v[88:91]
	v_mfma_f32_16x16x32_bf16 v[132:135], v[144:147], v[160:163], v[132:135]
	v_mfma_f32_16x16x32_bf16 v[128:131], v[152:155], v[160:163], v[128:131]
	v_mfma_f32_16x16x32_bf16 v[116:119], v[144:147], v[168:171], v[116:119]
	v_mfma_f32_16x16x32_bf16 v[112:115], v[152:155], v[168:171], v[112:115]
	v_mfma_f32_16x16x32_bf16 v[100:103], v[144:147], v[176:179], v[100:103]
	v_mfma_f32_16x16x32_bf16 v[96:99], v[152:155], v[176:179], v[96:99]
	v_mfma_f32_16x16x32_bf16 v[84:87], v[144:147], v[184:187], v[84:87]
	v_mfma_f32_16x16x32_bf16 v[80:83], v[152:155], v[184:187], v[80:83]
	v_mfma_f32_16x16x32_bf16 v[132:135], v[148:151], v[164:167], v[132:135]
	v_mfma_f32_16x16x32_bf16 v[128:131], v[156:159], v[164:167], v[128:131]
	v_mfma_f32_16x16x32_bf16 v[116:119], v[148:151], v[172:175], v[116:119]
	v_mfma_f32_16x16x32_bf16 v[112:115], v[156:159], v[172:175], v[112:115]
	v_mfma_f32_16x16x32_bf16 v[100:103], v[148:151], v[180:183], v[100:103]
	v_mfma_f32_16x16x32_bf16 v[96:99], v[156:159], v[180:183], v[96:99]
	v_mfma_f32_16x16x32_bf16 v[84:87], v[148:151], v[188:191], v[84:87]
	v_mfma_f32_16x16x32_bf16 v[80:83], v[156:159], v[188:191], v[80:83]
	s_barrier
	s_add_i32 s52, s78, s54
	s_mov_b32 m0, s52
	ds_read_b128 v[160:163], v243 offset:49152
	ds_read_b128 v[164:167], v243 offset:50176
	ds_read_b128 v[168:171], v243 offset:51200
	ds_read_b128 v[172:175], v243 offset:52224
	ds_read_b128 v[176:179], v243 offset:53248
	ds_read_b128 v[180:183], v243 offset:54272
	ds_read_b128 v[184:187], v243 offset:55296
	ds_read_b128 v[188:191], v243 offset:56320
	global_load_lds_dwordx4 v210, s[98:99]
	s_add_i32 m0, s52, 0x2000
	s_add_u32 s50, s50, 0x200080
	s_addc_u32 s51, s51, 0
	s_add_i32 s52, s79, s54
	global_load_lds_dwordx4 v214, s[98:99]
	s_mov_b32 m0, s52
	s_nop 0
	global_load_lds_dwordx4 v210, s[50:51]
	s_add_i32 m0, s52, 0x2000
	s_nop 0
	global_load_lds_dwordx4 v214, s[50:51]
	s_mov_b32 m0, s63
	s_nop 0
	global_load_lds_dwordx4 v208, s[100:101]
	s_mov_b32 m0, s68
	s_nop 0
	global_load_lds_dwordx4 v212, s[100:101]
	s_waitcnt vmcnt(8)
	s_waitcnt lgkmcnt(0)
	s_barrier
	s_waitcnt lgkmcnt(0)
	v_mfma_f32_16x16x32_bf16 v[76:79], v[56:59], v[160:163], v[76:79]
	v_mfma_f32_16x16x32_bf16 v[72:75], v[64:67], v[160:163], v[72:75]
	v_mfma_f32_16x16x32_bf16 v[44:47], v[56:59], v[168:171], v[44:47]
	v_mfma_f32_16x16x32_bf16 v[40:43], v[64:67], v[168:171], v[40:43]
	v_mfma_f32_16x16x32_bf16 v[28:31], v[56:59], v[176:179], v[28:31]
	v_mfma_f32_16x16x32_bf16 v[24:27], v[64:67], v[176:179], v[24:27]
	v_mfma_f32_16x16x32_bf16 v[12:15], v[56:59], v[184:187], v[12:15]
	v_mfma_f32_16x16x32_bf16 v[8:11], v[64:67], v[184:187], v[8:11]
	v_mfma_f32_16x16x32_bf16 v[76:79], v[60:63], v[164:167], v[76:79]
	v_mfma_f32_16x16x32_bf16 v[72:75], v[68:71], v[164:167], v[72:75]
	v_mfma_f32_16x16x32_bf16 v[44:47], v[60:63], v[172:175], v[44:47]
	v_mfma_f32_16x16x32_bf16 v[40:43], v[68:71], v[172:175], v[40:43]
	v_mfma_f32_16x16x32_bf16 v[28:31], v[60:63], v[180:183], v[28:31]
	v_mfma_f32_16x16x32_bf16 v[24:27], v[68:71], v[180:183], v[24:27]
	v_mfma_f32_16x16x32_bf16 v[12:15], v[60:63], v[188:191], v[12:15]
	v_mfma_f32_16x16x32_bf16 v[8:11], v[68:71], v[188:191], v[8:11]
	v_mfma_f32_16x16x32_bf16 v[52:55], v[144:147], v[160:163], v[52:55]
	v_mfma_f32_16x16x32_bf16 v[48:51], v[152:155], v[160:163], v[48:51]
	v_mfma_f32_16x16x32_bf16 v[36:39], v[144:147], v[168:171], v[36:39]
	v_mfma_f32_16x16x32_bf16 v[32:35], v[152:155], v[168:171], v[32:35]
	v_mfma_f32_16x16x32_bf16 v[20:23], v[144:147], v[176:179], v[20:23]
	v_mfma_f32_16x16x32_bf16 v[16:19], v[152:155], v[176:179], v[16:19]
	v_mfma_f32_16x16x32_bf16 v[4:7], v[144:147], v[184:187], v[4:7]
	v_mfma_f32_16x16x32_bf16 v[0:3], v[152:155], v[184:187], v[0:3]
	v_mfma_f32_16x16x32_bf16 v[52:55], v[148:151], v[164:167], v[52:55]
	v_mfma_f32_16x16x32_bf16 v[48:51], v[156:159], v[164:167], v[48:51]
	v_mfma_f32_16x16x32_bf16 v[36:39], v[148:151], v[172:175], v[36:39]
	v_mfma_f32_16x16x32_bf16 v[32:35], v[156:159], v[172:175], v[32:35]
	v_mfma_f32_16x16x32_bf16 v[20:23], v[148:151], v[180:183], v[20:23]
	v_mfma_f32_16x16x32_bf16 v[16:19], v[156:159], v[180:183], v[16:19]
	v_mfma_f32_16x16x32_bf16 v[4:7], v[148:151], v[188:191], v[4:7]
	v_mfma_f32_16x16x32_bf16 v[0:3], v[156:159], v[188:191], v[0:3]
	s_barrier
	s_add_i32 s77, s77, 2
	s_add_u32 s46, s46, 0x100
	s_addc_u32 s47, s47, 0
	s_add_u32 s75, s75, 0x100
	s_addc_u32 s76, s76, 0
	s_cmpk_gt_u32 s77, 0x7d
	s_cbranch_scc0 .LBB0_815
	s_setprio 0
	s_and_b64 vcc, exec, s[14:15]
	s_cbranch_vccz .LBB0_818
	s_barrier
